# ccpack: scanner reads two steps' c1 as one ds_read_b64 (CC buffer re-laid out c1[32] | c2[32]; c2 is read only by the producer's y write-back)
# speedup vs baseline: 1.0040x; 1.0040x over previous
.LBB0_726:
	s_and_b32 s1, s0, 1
	s_lshl_b32 s31, s1, 8
	s_mul_i32 s30, s1, 0xa000
	s_add_i32 s31, s31, 0x18000
	v_add_u32_e32 v6, s30, v151
	v_mov_b32_e32 v8, s31
	v_lshl_add_u32 v7, s1, 13, v0
	v_lshl_add_u32 v9, s1, 11, v39
	v_add_u32_e32 v22, 0x400, v9
	ds_read_b128 v[58:61], v6
	ds_read_b128 v[62:65], v6 offset:16
	ds_read_b128 v[66:69], v6 offset:32
	ds_read_b128 v[70:73], v6 offset:48
	ds_read_b128 v[74:77], v6 offset:64
	ds_read2st64_b32 v[118:119], v7 offset1:1
	ds_read_b64 v[120:121], v8
	ds_read_b128 v[78:81], v6 offset:1280
	ds_read_b128 v[82:85], v6 offset:1296
	ds_read_b128 v[86:89], v6 offset:1312
	ds_read_b128 v[90:93], v6 offset:1328
	ds_read_b128 v[94:97], v6 offset:1344
	ds_read_b128 v[98:101], v6 offset:2560
	ds_read_b128 v[102:105], v6 offset:2576
	ds_read_b128 v[106:109], v6 offset:2592
	ds_read_b128 v[110:113], v6 offset:2608
	ds_read_b128 v[114:117], v6 offset:2624
	ds_read2st64_b32 v[206:207], v7 offset0:2 offset1:3
	ds_read_b64 v[208:209], v8 offset:8
	s_waitcnt lgkmcnt(12)
	v_pk_mul_f32 v[10:11], v[2:3], v[58:59] op_sel_hi:[0,1]
	v_pk_fma_f32 v[10:11], v[2:3], v[60:61], v[10:11] op_sel:[1,0,0] op_sel_hi:[1,1,1]
	v_pk_fma_f32 v[10:11], v[4:5], v[62:63], v[10:11] op_sel_hi:[0,1,1]
	v_pk_fma_f32 v[10:11], v[4:5], v[64:65], v[10:11] op_sel:[1,0,0] op_sel_hi:[1,1,1]
	v_pk_mul_f32 v[18:19], v[74:75], v[118:119] op_sel_hi:[1,0]
	v_pk_mul_f32 v[20:21], v[76:77], v[118:119] op_sel_hi:[1,0]
	v_add_f32_dpp v10, v10, v10 quad_perm:[1,0,3,2] row_mask:0xf bank_mask:0xf bound_ctrl:1
	v_add_f32_dpp v11, v11, v11 quad_perm:[1,0,3,2] row_mask:0xf bank_mask:0xf bound_ctrl:1
	v_pk_fma_f32 v[18:19], v[2:3], v[66:67], v[18:19]
	v_add_f32_dpp v10, v10, v10 quad_perm:[2,3,0,1] row_mask:0xf bank_mask:0xf bound_ctrl:1
	v_add_f32_dpp v11, v11, v11 quad_perm:[2,3,0,1] row_mask:0xf bank_mask:0xf bound_ctrl:1
	v_pk_fma_f32 v[20:21], v[4:5], v[68:69], v[20:21]
	v_add_f32_dpp v10, v10, v10 row_half_mirror row_mask:0xf bank_mask:0xf bound_ctrl:1
	v_add_f32_dpp v11, v11, v11 row_half_mirror row_mask:0xf bank_mask:0xf bound_ctrl:1
	s_nop 0
	v_add_f32_dpp v10, v10, v10 row_mirror row_mask:0xf bank_mask:0xf bound_ctrl:1
	v_add_f32_dpp v11, v11, v11 row_mirror row_mask:0xf bank_mask:0xf bound_ctrl:1
	v_pk_fma_f32 v[2:3], v[70:71], v[10:11], v[18:19] op_sel_hi:[1,0,1]
	v_pk_fma_f32 v[4:5], v[72:73], v[10:11], v[20:21] op_sel_hi:[1,0,1]
	v_fmac_f32_e32 v11, v120, v10
	ds_read_b128 v[186:189], v6 offset:3840
	ds_read_b128 v[190:193], v6 offset:3856
	ds_read_b128 v[194:197], v6 offset:3872
	ds_read_b128 v[198:201], v6 offset:3888
	ds_read_b128 v[202:205], v6 offset:3904
	s_waitcnt lgkmcnt(12)
	v_pk_mul_f32 v[12:13], v[2:3], v[78:79] op_sel_hi:[0,1]
	v_pk_fma_f32 v[12:13], v[2:3], v[80:81], v[12:13] op_sel:[1,0,0] op_sel_hi:[1,1,1]
	v_pk_fma_f32 v[12:13], v[4:5], v[82:83], v[12:13] op_sel_hi:[0,1,1]
	v_pk_fma_f32 v[12:13], v[4:5], v[84:85], v[12:13] op_sel:[1,0,0] op_sel_hi:[1,1,1]
	v_pk_mul_f32 v[18:19], v[94:95], v[118:119] op_sel:[0,1] op_sel_hi:[1,1]
	v_pk_mul_f32 v[20:21], v[96:97], v[118:119] op_sel:[0,1] op_sel_hi:[1,1]
	v_add_f32_dpp v12, v12, v12 quad_perm:[1,0,3,2] row_mask:0xf bank_mask:0xf bound_ctrl:1
	v_add_f32_dpp v13, v13, v13 quad_perm:[1,0,3,2] row_mask:0xf bank_mask:0xf bound_ctrl:1
	v_pk_fma_f32 v[18:19], v[2:3], v[86:87], v[18:19]
	v_add_f32_dpp v12, v12, v12 quad_perm:[2,3,0,1] row_mask:0xf bank_mask:0xf bound_ctrl:1
	v_add_f32_dpp v13, v13, v13 quad_perm:[2,3,0,1] row_mask:0xf bank_mask:0xf bound_ctrl:1
	v_pk_fma_f32 v[20:21], v[4:5], v[88:89], v[20:21]
	v_add_f32_dpp v12, v12, v12 row_half_mirror row_mask:0xf bank_mask:0xf bound_ctrl:1
	v_add_f32_dpp v13, v13, v13 row_half_mirror row_mask:0xf bank_mask:0xf bound_ctrl:1
	s_nop 0
	v_add_f32_dpp v12, v12, v12 row_mirror row_mask:0xf bank_mask:0xf bound_ctrl:1
	v_add_f32_dpp v13, v13, v13 row_mirror row_mask:0xf bank_mask:0xf bound_ctrl:1
	v_pk_fma_f32 v[2:3], v[90:91], v[12:13], v[18:19] op_sel_hi:[1,0,1]
	v_pk_fma_f32 v[4:5], v[92:93], v[12:13], v[20:21] op_sel_hi:[1,0,1]
	v_fmac_f32_e32 v13, v121, v12
	ds_write2_b32 v9, v11, v13 offset1:16
	ds_read_b128 v[58:61], v6 offset:5120
	ds_read_b128 v[62:65], v6 offset:5136
	ds_read_b128 v[66:69], v6 offset:5152
	ds_read_b128 v[70:73], v6 offset:5168
	ds_read_b128 v[74:77], v6 offset:5184
	ds_read2st64_b32 v[118:119], v7 offset0:4 offset1:5
	ds_read_b64 v[120:121], v8 offset:16
	s_waitcnt lgkmcnt(13)
	v_pk_mul_f32 v[14:15], v[2:3], v[98:99] op_sel_hi:[0,1]
	v_pk_fma_f32 v[14:15], v[2:3], v[100:101], v[14:15] op_sel:[1,0,0] op_sel_hi:[1,1,1]
	v_pk_fma_f32 v[14:15], v[4:5], v[102:103], v[14:15] op_sel_hi:[0,1,1]
	v_pk_fma_f32 v[14:15], v[4:5], v[104:105], v[14:15] op_sel:[1,0,0] op_sel_hi:[1,1,1]
	v_pk_mul_f32 v[18:19], v[114:115], v[206:207] op_sel_hi:[1,0]
	v_pk_mul_f32 v[20:21], v[116:117], v[206:207] op_sel_hi:[1,0]
	v_add_f32_dpp v14, v14, v14 quad_perm:[1,0,3,2] row_mask:0xf bank_mask:0xf bound_ctrl:1
	v_add_f32_dpp v15, v15, v15 quad_perm:[1,0,3,2] row_mask:0xf bank_mask:0xf bound_ctrl:1
	v_pk_fma_f32 v[18:19], v[2:3], v[106:107], v[18:19]
	v_add_f32_dpp v14, v14, v14 quad_perm:[2,3,0,1] row_mask:0xf bank_mask:0xf bound_ctrl:1
	v_add_f32_dpp v15, v15, v15 quad_perm:[2,3,0,1] row_mask:0xf bank_mask:0xf bound_ctrl:1
	v_pk_fma_f32 v[20:21], v[4:5], v[108:109], v[20:21]
	v_add_f32_dpp v14, v14, v14 row_half_mirror row_mask:0xf bank_mask:0xf bound_ctrl:1
	v_add_f32_dpp v15, v15, v15 row_half_mirror row_mask:0xf bank_mask:0xf bound_ctrl:1
	s_nop 0
	v_add_f32_dpp v14, v14, v14 row_mirror row_mask:0xf bank_mask:0xf bound_ctrl:1
	v_add_f32_dpp v15, v15, v15 row_mirror row_mask:0xf bank_mask:0xf bound_ctrl:1
	v_pk_fma_f32 v[2:3], v[110:111], v[14:15], v[18:19] op_sel_hi:[1,0,1]
	v_pk_fma_f32 v[4:5], v[112:113], v[14:15], v[20:21] op_sel_hi:[1,0,1]
	v_fmac_f32_e32 v15, v208, v14
	ds_read_b128 v[78:81], v6 offset:6400
	ds_read_b128 v[82:85], v6 offset:6416
	ds_read_b128 v[86:89], v6 offset:6432
	ds_read_b128 v[90:93], v6 offset:6448
	ds_read_b128 v[94:97], v6 offset:6464
	s_waitcnt lgkmcnt(13)
	v_pk_mul_f32 v[16:17], v[2:3], v[186:187] op_sel_hi:[0,1]
	v_pk_fma_f32 v[16:17], v[2:3], v[188:189], v[16:17] op_sel:[1,0,0] op_sel_hi:[1,1,1]
	v_pk_fma_f32 v[16:17], v[4:5], v[190:191], v[16:17] op_sel_hi:[0,1,1]
	v_pk_fma_f32 v[16:17], v[4:5], v[192:193], v[16:17] op_sel:[1,0,0] op_sel_hi:[1,1,1]
	v_pk_mul_f32 v[18:19], v[202:203], v[206:207] op_sel:[0,1] op_sel_hi:[1,1]
	v_pk_mul_f32 v[20:21], v[204:205], v[206:207] op_sel:[0,1] op_sel_hi:[1,1]
	v_add_f32_dpp v16, v16, v16 quad_perm:[1,0,3,2] row_mask:0xf bank_mask:0xf bound_ctrl:1
	v_add_f32_dpp v17, v17, v17 quad_perm:[1,0,3,2] row_mask:0xf bank_mask:0xf bound_ctrl:1
	v_pk_fma_f32 v[18:19], v[2:3], v[194:195], v[18:19]
	v_add_f32_dpp v16, v16, v16 quad_perm:[2,3,0,1] row_mask:0xf bank_mask:0xf bound_ctrl:1
	v_add_f32_dpp v17, v17, v17 quad_perm:[2,3,0,1] row_mask:0xf bank_mask:0xf bound_ctrl:1
	v_pk_fma_f32 v[20:21], v[4:5], v[196:197], v[20:21]
	v_add_f32_dpp v16, v16, v16 row_half_mirror row_mask:0xf bank_mask:0xf bound_ctrl:1
	v_add_f32_dpp v17, v17, v17 row_half_mirror row_mask:0xf bank_mask:0xf bound_ctrl:1
	s_nop 0
	v_add_f32_dpp v16, v16, v16 row_mirror row_mask:0xf bank_mask:0xf bound_ctrl:1
	v_add_f32_dpp v17, v17, v17 row_mirror row_mask:0xf bank_mask:0xf bound_ctrl:1
	v_pk_fma_f32 v[2:3], v[198:199], v[16:17], v[18:19] op_sel_hi:[1,0,1]
	v_pk_fma_f32 v[4:5], v[200:201], v[16:17], v[20:21] op_sel_hi:[1,0,1]
	v_fmac_f32_e32 v17, v209, v16
	ds_write2_b32 v9, v15, v17 offset0:32 offset1:48
	ds_read_b128 v[98:101], v6 offset:7680
	ds_read_b128 v[102:105], v6 offset:7696
	ds_read_b128 v[106:109], v6 offset:7712
	ds_read_b128 v[110:113], v6 offset:7728
	ds_read_b128 v[114:117], v6 offset:7744
	ds_read2st64_b32 v[206:207], v7 offset0:6 offset1:7
	ds_read_b64 v[208:209], v8 offset:24
	s_waitcnt lgkmcnt(13)
	v_pk_mul_f32 v[10:11], v[2:3], v[58:59] op_sel_hi:[0,1]
	v_pk_fma_f32 v[10:11], v[2:3], v[60:61], v[10:11] op_sel:[1,0,0] op_sel_hi:[1,1,1]
	v_pk_fma_f32 v[10:11], v[4:5], v[62:63], v[10:11] op_sel_hi:[0,1,1]
	v_pk_fma_f32 v[10:11], v[4:5], v[64:65], v[10:11] op_sel:[1,0,0] op_sel_hi:[1,1,1]
	v_pk_mul_f32 v[18:19], v[74:75], v[118:119] op_sel_hi:[1,0]
	v_pk_mul_f32 v[20:21], v[76:77], v[118:119] op_sel_hi:[1,0]
	v_add_f32_dpp v10, v10, v10 quad_perm:[1,0,3,2] row_mask:0xf bank_mask:0xf bound_ctrl:1
	v_add_f32_dpp v11, v11, v11 quad_perm:[1,0,3,2] row_mask:0xf bank_mask:0xf bound_ctrl:1
	v_pk_fma_f32 v[18:19], v[2:3], v[66:67], v[18:19]
	v_add_f32_dpp v10, v10, v10 quad_perm:[2,3,0,1] row_mask:0xf bank_mask:0xf bound_ctrl:1
	v_add_f32_dpp v11, v11, v11 quad_perm:[2,3,0,1] row_mask:0xf bank_mask:0xf bound_ctrl:1
	v_pk_fma_f32 v[20:21], v[4:5], v[68:69], v[20:21]
	v_add_f32_dpp v10, v10, v10 row_half_mirror row_mask:0xf bank_mask:0xf bound_ctrl:1
	v_add_f32_dpp v11, v11, v11 row_half_mirror row_mask:0xf bank_mask:0xf bound_ctrl:1
	s_nop 0
	v_add_f32_dpp v10, v10, v10 row_mirror row_mask:0xf bank_mask:0xf bound_ctrl:1
	v_add_f32_dpp v11, v11, v11 row_mirror row_mask:0xf bank_mask:0xf bound_ctrl:1
	v_pk_fma_f32 v[2:3], v[70:71], v[10:11], v[18:19] op_sel_hi:[1,0,1]
	v_pk_fma_f32 v[4:5], v[72:73], v[10:11], v[20:21] op_sel_hi:[1,0,1]
	v_fmac_f32_e32 v11, v120, v10
	ds_read_b128 v[186:189], v6 offset:8960
	ds_read_b128 v[190:193], v6 offset:8976
	ds_read_b128 v[194:197], v6 offset:8992
	ds_read_b128 v[198:201], v6 offset:9008
	ds_read_b128 v[202:205], v6 offset:9024
	s_waitcnt lgkmcnt(13)
	v_pk_mul_f32 v[12:13], v[2:3], v[78:79] op_sel_hi:[0,1]
	v_pk_fma_f32 v[12:13], v[2:3], v[80:81], v[12:13] op_sel:[1,0,0] op_sel_hi:[1,1,1]
	v_pk_fma_f32 v[12:13], v[4:5], v[82:83], v[12:13] op_sel_hi:[0,1,1]
	v_pk_fma_f32 v[12:13], v[4:5], v[84:85], v[12:13] op_sel:[1,0,0] op_sel_hi:[1,1,1]
	v_pk_mul_f32 v[18:19], v[94:95], v[118:119] op_sel:[0,1] op_sel_hi:[1,1]
	v_pk_mul_f32 v[20:21], v[96:97], v[118:119] op_sel:[0,1] op_sel_hi:[1,1]
	v_add_f32_dpp v12, v12, v12 quad_perm:[1,0,3,2] row_mask:0xf bank_mask:0xf bound_ctrl:1
	v_add_f32_dpp v13, v13, v13 quad_perm:[1,0,3,2] row_mask:0xf bank_mask:0xf bound_ctrl:1
	v_pk_fma_f32 v[18:19], v[2:3], v[86:87], v[18:19]
	v_add_f32_dpp v12, v12, v12 quad_perm:[2,3,0,1] row_mask:0xf bank_mask:0xf bound_ctrl:1
	v_add_f32_dpp v13, v13, v13 quad_perm:[2,3,0,1] row_mask:0xf bank_mask:0xf bound_ctrl:1
	v_pk_fma_f32 v[20:21], v[4:5], v[88:89], v[20:21]
	v_add_f32_dpp v12, v12, v12 row_half_mirror row_mask:0xf bank_mask:0xf bound_ctrl:1
	v_add_f32_dpp v13, v13, v13 row_half_mirror row_mask:0xf bank_mask:0xf bound_ctrl:1
	s_nop 0
	v_add_f32_dpp v12, v12, v12 row_mirror row_mask:0xf bank_mask:0xf bound_ctrl:1
	v_add_f32_dpp v13, v13, v13 row_mirror row_mask:0xf bank_mask:0xf bound_ctrl:1
	v_pk_fma_f32 v[2:3], v[90:91], v[12:13], v[18:19] op_sel_hi:[1,0,1]
	v_pk_fma_f32 v[4:5], v[92:93], v[12:13], v[20:21] op_sel_hi:[1,0,1]
	v_fmac_f32_e32 v13, v121, v12
	ds_write2_b32 v9, v11, v13 offset0:64 offset1:80
	ds_read_b128 v[58:61], v6 offset:10240
	ds_read_b128 v[62:65], v6 offset:10256
	ds_read_b128 v[66:69], v6 offset:10272
	ds_read_b128 v[70:73], v6 offset:10288
	ds_read_b128 v[74:77], v6 offset:10304
	ds_read2st64_b32 v[118:119], v7 offset0:8 offset1:9
	ds_read_b64 v[120:121], v8 offset:32
	s_waitcnt lgkmcnt(13)
	v_pk_mul_f32 v[14:15], v[2:3], v[98:99] op_sel_hi:[0,1]
	v_pk_fma_f32 v[14:15], v[2:3], v[100:101], v[14:15] op_sel:[1,0,0] op_sel_hi:[1,1,1]
	v_pk_fma_f32 v[14:15], v[4:5], v[102:103], v[14:15] op_sel_hi:[0,1,1]
	v_pk_fma_f32 v[14:15], v[4:5], v[104:105], v[14:15] op_sel:[1,0,0] op_sel_hi:[1,1,1]
	v_pk_mul_f32 v[18:19], v[114:115], v[206:207] op_sel_hi:[1,0]
	v_pk_mul_f32 v[20:21], v[116:117], v[206:207] op_sel_hi:[1,0]
	v_add_f32_dpp v14, v14, v14 quad_perm:[1,0,3,2] row_mask:0xf bank_mask:0xf bound_ctrl:1
	v_add_f32_dpp v15, v15, v15 quad_perm:[1,0,3,2] row_mask:0xf bank_mask:0xf bound_ctrl:1
	v_pk_fma_f32 v[18:19], v[2:3], v[106:107], v[18:19]
	v_add_f32_dpp v14, v14, v14 quad_perm:[2,3,0,1] row_mask:0xf bank_mask:0xf bound_ctrl:1
	v_add_f32_dpp v15, v15, v15 quad_perm:[2,3,0,1] row_mask:0xf bank_mask:0xf bound_ctrl:1
	v_pk_fma_f32 v[20:21], v[4:5], v[108:109], v[20:21]
	v_add_f32_dpp v14, v14, v14 row_half_mirror row_mask:0xf bank_mask:0xf bound_ctrl:1
	v_add_f32_dpp v15, v15, v15 row_half_mirror row_mask:0xf bank_mask:0xf bound_ctrl:1
	s_nop 0
	v_add_f32_dpp v14, v14, v14 row_mirror row_mask:0xf bank_mask:0xf bound_ctrl:1
	v_add_f32_dpp v15, v15, v15 row_mirror row_mask:0xf bank_mask:0xf bound_ctrl:1
	v_pk_fma_f32 v[2:3], v[110:111], v[14:15], v[18:19] op_sel_hi:[1,0,1]
	v_pk_fma_f32 v[4:5], v[112:113], v[14:15], v[20:21] op_sel_hi:[1,0,1]
	v_fmac_f32_e32 v15, v208, v14
	ds_read_b128 v[78:81], v6 offset:11520
	ds_read_b128 v[82:85], v6 offset:11536
	ds_read_b128 v[86:89], v6 offset:11552
	ds_read_b128 v[90:93], v6 offset:11568
	ds_read_b128 v[94:97], v6 offset:11584
	s_waitcnt lgkmcnt(13)
	v_pk_mul_f32 v[16:17], v[2:3], v[186:187] op_sel_hi:[0,1]
	v_pk_fma_f32 v[16:17], v[2:3], v[188:189], v[16:17] op_sel:[1,0,0] op_sel_hi:[1,1,1]
	v_pk_fma_f32 v[16:17], v[4:5], v[190:191], v[16:17] op_sel_hi:[0,1,1]
	v_pk_fma_f32 v[16:17], v[4:5], v[192:193], v[16:17] op_sel:[1,0,0] op_sel_hi:[1,1,1]
	v_pk_mul_f32 v[18:19], v[202:203], v[206:207] op_sel:[0,1] op_sel_hi:[1,1]
	v_pk_mul_f32 v[20:21], v[204:205], v[206:207] op_sel:[0,1] op_sel_hi:[1,1]
	v_add_f32_dpp v16, v16, v16 quad_perm:[1,0,3,2] row_mask:0xf bank_mask:0xf bound_ctrl:1
	v_add_f32_dpp v17, v17, v17 quad_perm:[1,0,3,2] row_mask:0xf bank_mask:0xf bound_ctrl:1
	v_pk_fma_f32 v[18:19], v[2:3], v[194:195], v[18:19]
	v_add_f32_dpp v16, v16, v16 quad_perm:[2,3,0,1] row_mask:0xf bank_mask:0xf bound_ctrl:1
	v_add_f32_dpp v17, v17, v17 quad_perm:[2,3,0,1] row_mask:0xf bank_mask:0xf bound_ctrl:1
	v_pk_fma_f32 v[20:21], v[4:5], v[196:197], v[20:21]
	v_add_f32_dpp v16, v16, v16 row_half_mirror row_mask:0xf bank_mask:0xf bound_ctrl:1
	v_add_f32_dpp v17, v17, v17 row_half_mirror row_mask:0xf bank_mask:0xf bound_ctrl:1
	s_nop 0
	v_add_f32_dpp v16, v16, v16 row_mirror row_mask:0xf bank_mask:0xf bound_ctrl:1
	v_add_f32_dpp v17, v17, v17 row_mirror row_mask:0xf bank_mask:0xf bound_ctrl:1
	v_pk_fma_f32 v[2:3], v[198:199], v[16:17], v[18:19] op_sel_hi:[1,0,1]
	v_pk_fma_f32 v[4:5], v[200:201], v[16:17], v[20:21] op_sel_hi:[1,0,1]
	v_fmac_f32_e32 v17, v209, v16
	ds_write2_b32 v9, v15, v17 offset0:96 offset1:112
	ds_read_b128 v[98:101], v6 offset:12800
	ds_read_b128 v[102:105], v6 offset:12816
	ds_read_b128 v[106:109], v6 offset:12832
	ds_read_b128 v[110:113], v6 offset:12848
	ds_read_b128 v[114:117], v6 offset:12864
	ds_read2st64_b32 v[206:207], v7 offset0:10 offset1:11
	ds_read_b64 v[208:209], v8 offset:40
	s_waitcnt lgkmcnt(13)
	v_pk_mul_f32 v[10:11], v[2:3], v[58:59] op_sel_hi:[0,1]
	v_pk_fma_f32 v[10:11], v[2:3], v[60:61], v[10:11] op_sel:[1,0,0] op_sel_hi:[1,1,1]
	v_pk_fma_f32 v[10:11], v[4:5], v[62:63], v[10:11] op_sel_hi:[0,1,1]
	v_pk_fma_f32 v[10:11], v[4:5], v[64:65], v[10:11] op_sel:[1,0,0] op_sel_hi:[1,1,1]
	v_pk_mul_f32 v[18:19], v[74:75], v[118:119] op_sel_hi:[1,0]
	v_pk_mul_f32 v[20:21], v[76:77], v[118:119] op_sel_hi:[1,0]
	v_add_f32_dpp v10, v10, v10 quad_perm:[1,0,3,2] row_mask:0xf bank_mask:0xf bound_ctrl:1
	v_add_f32_dpp v11, v11, v11 quad_perm:[1,0,3,2] row_mask:0xf bank_mask:0xf bound_ctrl:1
	v_pk_fma_f32 v[18:19], v[2:3], v[66:67], v[18:19]
	v_add_f32_dpp v10, v10, v10 quad_perm:[2,3,0,1] row_mask:0xf bank_mask:0xf bound_ctrl:1
	v_add_f32_dpp v11, v11, v11 quad_perm:[2,3,0,1] row_mask:0xf bank_mask:0xf bound_ctrl:1
	v_pk_fma_f32 v[20:21], v[4:5], v[68:69], v[20:21]
	v_add_f32_dpp v10, v10, v10 row_half_mirror row_mask:0xf bank_mask:0xf bound_ctrl:1
	v_add_f32_dpp v11, v11, v11 row_half_mirror row_mask:0xf bank_mask:0xf bound_ctrl:1
	s_nop 0
	v_add_f32_dpp v10, v10, v10 row_mirror row_mask:0xf bank_mask:0xf bound_ctrl:1
	v_add_f32_dpp v11, v11, v11 row_mirror row_mask:0xf bank_mask:0xf bound_ctrl:1
	v_pk_fma_f32 v[2:3], v[70:71], v[10:11], v[18:19] op_sel_hi:[1,0,1]
	v_pk_fma_f32 v[4:5], v[72:73], v[10:11], v[20:21] op_sel_hi:[1,0,1]
	v_fmac_f32_e32 v11, v120, v10
	ds_read_b128 v[186:189], v6 offset:14080
	ds_read_b128 v[190:193], v6 offset:14096
	ds_read_b128 v[194:197], v6 offset:14112
	ds_read_b128 v[198:201], v6 offset:14128
	ds_read_b128 v[202:205], v6 offset:14144
	s_waitcnt lgkmcnt(13)
	v_pk_mul_f32 v[12:13], v[2:3], v[78:79] op_sel_hi:[0,1]
	v_pk_fma_f32 v[12:13], v[2:3], v[80:81], v[12:13] op_sel:[1,0,0] op_sel_hi:[1,1,1]
	v_pk_fma_f32 v[12:13], v[4:5], v[82:83], v[12:13] op_sel_hi:[0,1,1]
	v_pk_fma_f32 v[12:13], v[4:5], v[84:85], v[12:13] op_sel:[1,0,0] op_sel_hi:[1,1,1]
	v_pk_mul_f32 v[18:19], v[94:95], v[118:119] op_sel:[0,1] op_sel_hi:[1,1]
	v_pk_mul_f32 v[20:21], v[96:97], v[118:119] op_sel:[0,1] op_sel_hi:[1,1]
	v_add_f32_dpp v12, v12, v12 quad_perm:[1,0,3,2] row_mask:0xf bank_mask:0xf bound_ctrl:1
	v_add_f32_dpp v13, v13, v13 quad_perm:[1,0,3,2] row_mask:0xf bank_mask:0xf bound_ctrl:1
	v_pk_fma_f32 v[18:19], v[2:3], v[86:87], v[18:19]
	v_add_f32_dpp v12, v12, v12 quad_perm:[2,3,0,1] row_mask:0xf bank_mask:0xf bound_ctrl:1
	v_add_f32_dpp v13, v13, v13 quad_perm:[2,3,0,1] row_mask:0xf bank_mask:0xf bound_ctrl:1
	v_pk_fma_f32 v[20:21], v[4:5], v[88:89], v[20:21]
	v_add_f32_dpp v12, v12, v12 row_half_mirror row_mask:0xf bank_mask:0xf bound_ctrl:1
	v_add_f32_dpp v13, v13, v13 row_half_mirror row_mask:0xf bank_mask:0xf bound_ctrl:1
	s_nop 0
	v_add_f32_dpp v12, v12, v12 row_mirror row_mask:0xf bank_mask:0xf bound_ctrl:1
	v_add_f32_dpp v13, v13, v13 row_mirror row_mask:0xf bank_mask:0xf bound_ctrl:1
	v_pk_fma_f32 v[2:3], v[90:91], v[12:13], v[18:19] op_sel_hi:[1,0,1]
	v_pk_fma_f32 v[4:5], v[92:93], v[12:13], v[20:21] op_sel_hi:[1,0,1]
	v_fmac_f32_e32 v13, v121, v12
	ds_write2_b32 v9, v11, v13 offset0:128 offset1:144
	ds_read_b128 v[58:61], v6 offset:15360
	ds_read_b128 v[62:65], v6 offset:15376
	ds_read_b128 v[66:69], v6 offset:15392
	ds_read_b128 v[70:73], v6 offset:15408
	ds_read_b128 v[74:77], v6 offset:15424
	ds_read2st64_b32 v[118:119], v7 offset0:12 offset1:13
	ds_read_b64 v[120:121], v8 offset:48
	s_waitcnt lgkmcnt(13)
	v_pk_mul_f32 v[14:15], v[2:3], v[98:99] op_sel_hi:[0,1]
	v_pk_fma_f32 v[14:15], v[2:3], v[100:101], v[14:15] op_sel:[1,0,0] op_sel_hi:[1,1,1]
	v_pk_fma_f32 v[14:15], v[4:5], v[102:103], v[14:15] op_sel_hi:[0,1,1]
	v_pk_fma_f32 v[14:15], v[4:5], v[104:105], v[14:15] op_sel:[1,0,0] op_sel_hi:[1,1,1]
	v_pk_mul_f32 v[18:19], v[114:115], v[206:207] op_sel_hi:[1,0]
	v_pk_mul_f32 v[20:21], v[116:117], v[206:207] op_sel_hi:[1,0]
	v_add_f32_dpp v14, v14, v14 quad_perm:[1,0,3,2] row_mask:0xf bank_mask:0xf bound_ctrl:1
	v_add_f32_dpp v15, v15, v15 quad_perm:[1,0,3,2] row_mask:0xf bank_mask:0xf bound_ctrl:1
	v_pk_fma_f32 v[18:19], v[2:3], v[106:107], v[18:19]
	v_add_f32_dpp v14, v14, v14 quad_perm:[2,3,0,1] row_mask:0xf bank_mask:0xf bound_ctrl:1
	v_add_f32_dpp v15, v15, v15 quad_perm:[2,3,0,1] row_mask:0xf bank_mask:0xf bound_ctrl:1
	v_pk_fma_f32 v[20:21], v[4:5], v[108:109], v[20:21]
	v_add_f32_dpp v14, v14, v14 row_half_mirror row_mask:0xf bank_mask:0xf bound_ctrl:1
	v_add_f32_dpp v15, v15, v15 row_half_mirror row_mask:0xf bank_mask:0xf bound_ctrl:1
	s_nop 0
	v_add_f32_dpp v14, v14, v14 row_mirror row_mask:0xf bank_mask:0xf bound_ctrl:1
	v_add_f32_dpp v15, v15, v15 row_mirror row_mask:0xf bank_mask:0xf bound_ctrl:1
	v_pk_fma_f32 v[2:3], v[110:111], v[14:15], v[18:19] op_sel_hi:[1,0,1]
	v_pk_fma_f32 v[4:5], v[112:113], v[14:15], v[20:21] op_sel_hi:[1,0,1]
	v_fmac_f32_e32 v15, v208, v14
	ds_read_b128 v[78:81], v6 offset:16640
	ds_read_b128 v[82:85], v6 offset:16656
	ds_read_b128 v[86:89], v6 offset:16672
	ds_read_b128 v[90:93], v6 offset:16688
	ds_read_b128 v[94:97], v6 offset:16704
	s_waitcnt lgkmcnt(13)
	v_pk_mul_f32 v[16:17], v[2:3], v[186:187] op_sel_hi:[0,1]
	v_pk_fma_f32 v[16:17], v[2:3], v[188:189], v[16:17] op_sel:[1,0,0] op_sel_hi:[1,1,1]
	v_pk_fma_f32 v[16:17], v[4:5], v[190:191], v[16:17] op_sel_hi:[0,1,1]
	v_pk_fma_f32 v[16:17], v[4:5], v[192:193], v[16:17] op_sel:[1,0,0] op_sel_hi:[1,1,1]
	v_pk_mul_f32 v[18:19], v[202:203], v[206:207] op_sel:[0,1] op_sel_hi:[1,1]
	v_pk_mul_f32 v[20:21], v[204:205], v[206:207] op_sel:[0,1] op_sel_hi:[1,1]
	v_add_f32_dpp v16, v16, v16 quad_perm:[1,0,3,2] row_mask:0xf bank_mask:0xf bound_ctrl:1
	v_add_f32_dpp v17, v17, v17 quad_perm:[1,0,3,2] row_mask:0xf bank_mask:0xf bound_ctrl:1
	v_pk_fma_f32 v[18:19], v[2:3], v[194:195], v[18:19]
	v_add_f32_dpp v16, v16, v16 quad_perm:[2,3,0,1] row_mask:0xf bank_mask:0xf bound_ctrl:1
	v_add_f32_dpp v17, v17, v17 quad_perm:[2,3,0,1] row_mask:0xf bank_mask:0xf bound_ctrl:1
	v_pk_fma_f32 v[20:21], v[4:5], v[196:197], v[20:21]
	v_add_f32_dpp v16, v16, v16 row_half_mirror row_mask:0xf bank_mask:0xf bound_ctrl:1
	v_add_f32_dpp v17, v17, v17 row_half_mirror row_mask:0xf bank_mask:0xf bound_ctrl:1
	s_nop 0
	v_add_f32_dpp v16, v16, v16 row_mirror row_mask:0xf bank_mask:0xf bound_ctrl:1
	v_add_f32_dpp v17, v17, v17 row_mirror row_mask:0xf bank_mask:0xf bound_ctrl:1
	v_pk_fma_f32 v[2:3], v[198:199], v[16:17], v[18:19] op_sel_hi:[1,0,1]
	v_pk_fma_f32 v[4:5], v[200:201], v[16:17], v[20:21] op_sel_hi:[1,0,1]
	v_fmac_f32_e32 v17, v209, v16
	ds_write2_b32 v9, v15, v17 offset0:160 offset1:176
	ds_read_b128 v[98:101], v6 offset:17920
	ds_read_b128 v[102:105], v6 offset:17936
	ds_read_b128 v[106:109], v6 offset:17952
	ds_read_b128 v[110:113], v6 offset:17968
	ds_read_b128 v[114:117], v6 offset:17984
	ds_read2st64_b32 v[206:207], v7 offset0:14 offset1:15
	ds_read_b64 v[208:209], v8 offset:56
	s_waitcnt lgkmcnt(13)
	v_pk_mul_f32 v[10:11], v[2:3], v[58:59] op_sel_hi:[0,1]
	v_pk_fma_f32 v[10:11], v[2:3], v[60:61], v[10:11] op_sel:[1,0,0] op_sel_hi:[1,1,1]
	v_pk_fma_f32 v[10:11], v[4:5], v[62:63], v[10:11] op_sel_hi:[0,1,1]
	v_pk_fma_f32 v[10:11], v[4:5], v[64:65], v[10:11] op_sel:[1,0,0] op_sel_hi:[1,1,1]
	v_pk_mul_f32 v[18:19], v[74:75], v[118:119] op_sel_hi:[1,0]
	v_pk_mul_f32 v[20:21], v[76:77], v[118:119] op_sel_hi:[1,0]
	v_add_f32_dpp v10, v10, v10 quad_perm:[1,0,3,2] row_mask:0xf bank_mask:0xf bound_ctrl:1
	v_add_f32_dpp v11, v11, v11 quad_perm:[1,0,3,2] row_mask:0xf bank_mask:0xf bound_ctrl:1
	v_pk_fma_f32 v[18:19], v[2:3], v[66:67], v[18:19]
	v_add_f32_dpp v10, v10, v10 quad_perm:[2,3,0,1] row_mask:0xf bank_mask:0xf bound_ctrl:1
	v_add_f32_dpp v11, v11, v11 quad_perm:[2,3,0,1] row_mask:0xf bank_mask:0xf bound_ctrl:1
	v_pk_fma_f32 v[20:21], v[4:5], v[68:69], v[20:21]
	v_add_f32_dpp v10, v10, v10 row_half_mirror row_mask:0xf bank_mask:0xf bound_ctrl:1
	v_add_f32_dpp v11, v11, v11 row_half_mirror row_mask:0xf bank_mask:0xf bound_ctrl:1
	s_nop 0
	v_add_f32_dpp v10, v10, v10 row_mirror row_mask:0xf bank_mask:0xf bound_ctrl:1
	v_add_f32_dpp v11, v11, v11 row_mirror row_mask:0xf bank_mask:0xf bound_ctrl:1
	v_pk_fma_f32 v[2:3], v[70:71], v[10:11], v[18:19] op_sel_hi:[1,0,1]
	v_pk_fma_f32 v[4:5], v[72:73], v[10:11], v[20:21] op_sel_hi:[1,0,1]
	v_fmac_f32_e32 v11, v120, v10
	ds_read_b128 v[186:189], v6 offset:19200
	ds_read_b128 v[190:193], v6 offset:19216
	ds_read_b128 v[194:197], v6 offset:19232
	ds_read_b128 v[198:201], v6 offset:19248
	ds_read_b128 v[202:205], v6 offset:19264
	s_waitcnt lgkmcnt(13)
	v_pk_mul_f32 v[12:13], v[2:3], v[78:79] op_sel_hi:[0,1]
	v_pk_fma_f32 v[12:13], v[2:3], v[80:81], v[12:13] op_sel:[1,0,0] op_sel_hi:[1,1,1]
	v_pk_fma_f32 v[12:13], v[4:5], v[82:83], v[12:13] op_sel_hi:[0,1,1]
	v_pk_fma_f32 v[12:13], v[4:5], v[84:85], v[12:13] op_sel:[1,0,0] op_sel_hi:[1,1,1]
	v_pk_mul_f32 v[18:19], v[94:95], v[118:119] op_sel:[0,1] op_sel_hi:[1,1]
	v_pk_mul_f32 v[20:21], v[96:97], v[118:119] op_sel:[0,1] op_sel_hi:[1,1]
	v_add_f32_dpp v12, v12, v12 quad_perm:[1,0,3,2] row_mask:0xf bank_mask:0xf bound_ctrl:1
	v_add_f32_dpp v13, v13, v13 quad_perm:[1,0,3,2] row_mask:0xf bank_mask:0xf bound_ctrl:1
	v_pk_fma_f32 v[18:19], v[2:3], v[86:87], v[18:19]
	v_add_f32_dpp v12, v12, v12 quad_perm:[2,3,0,1] row_mask:0xf bank_mask:0xf bound_ctrl:1
	v_add_f32_dpp v13, v13, v13 quad_perm:[2,3,0,1] row_mask:0xf bank_mask:0xf bound_ctrl:1
	v_pk_fma_f32 v[20:21], v[4:5], v[88:89], v[20:21]
	v_add_f32_dpp v12, v12, v12 row_half_mirror row_mask:0xf bank_mask:0xf bound_ctrl:1
	v_add_f32_dpp v13, v13, v13 row_half_mirror row_mask:0xf bank_mask:0xf bound_ctrl:1
	s_nop 0
	v_add_f32_dpp v12, v12, v12 row_mirror row_mask:0xf bank_mask:0xf bound_ctrl:1
	v_add_f32_dpp v13, v13, v13 row_mirror row_mask:0xf bank_mask:0xf bound_ctrl:1
	v_pk_fma_f32 v[2:3], v[90:91], v[12:13], v[18:19] op_sel_hi:[1,0,1]
	v_pk_fma_f32 v[4:5], v[92:93], v[12:13], v[20:21] op_sel_hi:[1,0,1]
	v_fmac_f32_e32 v13, v121, v12
	ds_write2_b32 v9, v11, v13 offset0:192 offset1:208
	ds_read_b128 v[58:61], v6 offset:20480
	ds_read_b128 v[62:65], v6 offset:20496
	ds_read_b128 v[66:69], v6 offset:20512
	ds_read_b128 v[70:73], v6 offset:20528
	ds_read_b128 v[74:77], v6 offset:20544
	ds_read2st64_b32 v[118:119], v7 offset0:16 offset1:17
	ds_read_b64 v[120:121], v8 offset:64
	s_waitcnt lgkmcnt(13)
	v_pk_mul_f32 v[14:15], v[2:3], v[98:99] op_sel_hi:[0,1]
	v_pk_fma_f32 v[14:15], v[2:3], v[100:101], v[14:15] op_sel:[1,0,0] op_sel_hi:[1,1,1]
	v_pk_fma_f32 v[14:15], v[4:5], v[102:103], v[14:15] op_sel_hi:[0,1,1]
	v_pk_fma_f32 v[14:15], v[4:5], v[104:105], v[14:15] op_sel:[1,0,0] op_sel_hi:[1,1,1]
	v_pk_mul_f32 v[18:19], v[114:115], v[206:207] op_sel_hi:[1,0]
	v_pk_mul_f32 v[20:21], v[116:117], v[206:207] op_sel_hi:[1,0]
	v_add_f32_dpp v14, v14, v14 quad_perm:[1,0,3,2] row_mask:0xf bank_mask:0xf bound_ctrl:1
	v_add_f32_dpp v15, v15, v15 quad_perm:[1,0,3,2] row_mask:0xf bank_mask:0xf bound_ctrl:1
	v_pk_fma_f32 v[18:19], v[2:3], v[106:107], v[18:19]
	v_add_f32_dpp v14, v14, v14 quad_perm:[2,3,0,1] row_mask:0xf bank_mask:0xf bound_ctrl:1
	v_add_f32_dpp v15, v15, v15 quad_perm:[2,3,0,1] row_mask:0xf bank_mask:0xf bound_ctrl:1
	v_pk_fma_f32 v[20:21], v[4:5], v[108:109], v[20:21]
	v_add_f32_dpp v14, v14, v14 row_half_mirror row_mask:0xf bank_mask:0xf bound_ctrl:1
	v_add_f32_dpp v15, v15, v15 row_half_mirror row_mask:0xf bank_mask:0xf bound_ctrl:1
	s_nop 0
	v_add_f32_dpp v14, v14, v14 row_mirror row_mask:0xf bank_mask:0xf bound_ctrl:1
	v_add_f32_dpp v15, v15, v15 row_mirror row_mask:0xf bank_mask:0xf bound_ctrl:1
	v_pk_fma_f32 v[2:3], v[110:111], v[14:15], v[18:19] op_sel_hi:[1,0,1]
	v_pk_fma_f32 v[4:5], v[112:113], v[14:15], v[20:21] op_sel_hi:[1,0,1]
	v_fmac_f32_e32 v15, v208, v14
	ds_read_b128 v[78:81], v6 offset:21760
	ds_read_b128 v[82:85], v6 offset:21776
	ds_read_b128 v[86:89], v6 offset:21792
	ds_read_b128 v[90:93], v6 offset:21808
	ds_read_b128 v[94:97], v6 offset:21824
	s_waitcnt lgkmcnt(13)
	v_pk_mul_f32 v[16:17], v[2:3], v[186:187] op_sel_hi:[0,1]
	v_pk_fma_f32 v[16:17], v[2:3], v[188:189], v[16:17] op_sel:[1,0,0] op_sel_hi:[1,1,1]
	v_pk_fma_f32 v[16:17], v[4:5], v[190:191], v[16:17] op_sel_hi:[0,1,1]
	v_pk_fma_f32 v[16:17], v[4:5], v[192:193], v[16:17] op_sel:[1,0,0] op_sel_hi:[1,1,1]
	v_pk_mul_f32 v[18:19], v[202:203], v[206:207] op_sel:[0,1] op_sel_hi:[1,1]
	v_pk_mul_f32 v[20:21], v[204:205], v[206:207] op_sel:[0,1] op_sel_hi:[1,1]
	v_add_f32_dpp v16, v16, v16 quad_perm:[1,0,3,2] row_mask:0xf bank_mask:0xf bound_ctrl:1
	v_add_f32_dpp v17, v17, v17 quad_perm:[1,0,3,2] row_mask:0xf bank_mask:0xf bound_ctrl:1
	v_pk_fma_f32 v[18:19], v[2:3], v[194:195], v[18:19]
	v_add_f32_dpp v16, v16, v16 quad_perm:[2,3,0,1] row_mask:0xf bank_mask:0xf bound_ctrl:1
	v_add_f32_dpp v17, v17, v17 quad_perm:[2,3,0,1] row_mask:0xf bank_mask:0xf bound_ctrl:1
	v_pk_fma_f32 v[20:21], v[4:5], v[196:197], v[20:21]
	v_add_f32_dpp v16, v16, v16 row_half_mirror row_mask:0xf bank_mask:0xf bound_ctrl:1
	v_add_f32_dpp v17, v17, v17 row_half_mirror row_mask:0xf bank_mask:0xf bound_ctrl:1
	s_nop 0
	v_add_f32_dpp v16, v16, v16 row_mirror row_mask:0xf bank_mask:0xf bound_ctrl:1
	v_add_f32_dpp v17, v17, v17 row_mirror row_mask:0xf bank_mask:0xf bound_ctrl:1
	v_pk_fma_f32 v[2:3], v[198:199], v[16:17], v[18:19] op_sel_hi:[1,0,1]
	v_pk_fma_f32 v[4:5], v[200:201], v[16:17], v[20:21] op_sel_hi:[1,0,1]
	v_fmac_f32_e32 v17, v209, v16
	ds_write2_b32 v9, v15, v17 offset0:224 offset1:240
	ds_read_b128 v[98:101], v6 offset:23040
	ds_read_b128 v[102:105], v6 offset:23056
	ds_read_b128 v[106:109], v6 offset:23072
	ds_read_b128 v[110:113], v6 offset:23088
	ds_read_b128 v[114:117], v6 offset:23104
	ds_read2st64_b32 v[206:207], v7 offset0:18 offset1:19
	ds_read_b64 v[208:209], v8 offset:72
	s_waitcnt lgkmcnt(13)
	v_pk_mul_f32 v[10:11], v[2:3], v[58:59] op_sel_hi:[0,1]
	v_pk_fma_f32 v[10:11], v[2:3], v[60:61], v[10:11] op_sel:[1,0,0] op_sel_hi:[1,1,1]
	v_pk_fma_f32 v[10:11], v[4:5], v[62:63], v[10:11] op_sel_hi:[0,1,1]
	v_pk_fma_f32 v[10:11], v[4:5], v[64:65], v[10:11] op_sel:[1,0,0] op_sel_hi:[1,1,1]
	v_pk_mul_f32 v[18:19], v[74:75], v[118:119] op_sel_hi:[1,0]
	v_pk_mul_f32 v[20:21], v[76:77], v[118:119] op_sel_hi:[1,0]
	v_add_f32_dpp v10, v10, v10 quad_perm:[1,0,3,2] row_mask:0xf bank_mask:0xf bound_ctrl:1
	v_add_f32_dpp v11, v11, v11 quad_perm:[1,0,3,2] row_mask:0xf bank_mask:0xf bound_ctrl:1
	v_pk_fma_f32 v[18:19], v[2:3], v[66:67], v[18:19]
	v_add_f32_dpp v10, v10, v10 quad_perm:[2,3,0,1] row_mask:0xf bank_mask:0xf bound_ctrl:1
	v_add_f32_dpp v11, v11, v11 quad_perm:[2,3,0,1] row_mask:0xf bank_mask:0xf bound_ctrl:1
	v_pk_fma_f32 v[20:21], v[4:5], v[68:69], v[20:21]
	v_add_f32_dpp v10, v10, v10 row_half_mirror row_mask:0xf bank_mask:0xf bound_ctrl:1
	v_add_f32_dpp v11, v11, v11 row_half_mirror row_mask:0xf bank_mask:0xf bound_ctrl:1
	s_nop 0
	v_add_f32_dpp v10, v10, v10 row_mirror row_mask:0xf bank_mask:0xf bound_ctrl:1
	v_add_f32_dpp v11, v11, v11 row_mirror row_mask:0xf bank_mask:0xf bound_ctrl:1
	v_pk_fma_f32 v[2:3], v[70:71], v[10:11], v[18:19] op_sel_hi:[1,0,1]
	v_pk_fma_f32 v[4:5], v[72:73], v[10:11], v[20:21] op_sel_hi:[1,0,1]
	v_fmac_f32_e32 v11, v120, v10
	ds_read_b128 v[186:189], v6 offset:24320
	ds_read_b128 v[190:193], v6 offset:24336
	ds_read_b128 v[194:197], v6 offset:24352
	ds_read_b128 v[198:201], v6 offset:24368
	ds_read_b128 v[202:205], v6 offset:24384
	s_waitcnt lgkmcnt(13)
	v_pk_mul_f32 v[12:13], v[2:3], v[78:79] op_sel_hi:[0,1]
	v_pk_fma_f32 v[12:13], v[2:3], v[80:81], v[12:13] op_sel:[1,0,0] op_sel_hi:[1,1,1]
	v_pk_fma_f32 v[12:13], v[4:5], v[82:83], v[12:13] op_sel_hi:[0,1,1]
	v_pk_fma_f32 v[12:13], v[4:5], v[84:85], v[12:13] op_sel:[1,0,0] op_sel_hi:[1,1,1]
	v_pk_mul_f32 v[18:19], v[94:95], v[118:119] op_sel:[0,1] op_sel_hi:[1,1]
	v_pk_mul_f32 v[20:21], v[96:97], v[118:119] op_sel:[0,1] op_sel_hi:[1,1]
	v_add_f32_dpp v12, v12, v12 quad_perm:[1,0,3,2] row_mask:0xf bank_mask:0xf bound_ctrl:1
	v_add_f32_dpp v13, v13, v13 quad_perm:[1,0,3,2] row_mask:0xf bank_mask:0xf bound_ctrl:1
	v_pk_fma_f32 v[18:19], v[2:3], v[86:87], v[18:19]
	v_add_f32_dpp v12, v12, v12 quad_perm:[2,3,0,1] row_mask:0xf bank_mask:0xf bound_ctrl:1
	v_add_f32_dpp v13, v13, v13 quad_perm:[2,3,0,1] row_mask:0xf bank_mask:0xf bound_ctrl:1
	v_pk_fma_f32 v[20:21], v[4:5], v[88:89], v[20:21]
	v_add_f32_dpp v12, v12, v12 row_half_mirror row_mask:0xf bank_mask:0xf bound_ctrl:1
	v_add_f32_dpp v13, v13, v13 row_half_mirror row_mask:0xf bank_mask:0xf bound_ctrl:1
	s_nop 0
	v_add_f32_dpp v12, v12, v12 row_mirror row_mask:0xf bank_mask:0xf bound_ctrl:1
	v_add_f32_dpp v13, v13, v13 row_mirror row_mask:0xf bank_mask:0xf bound_ctrl:1
	v_pk_fma_f32 v[2:3], v[90:91], v[12:13], v[18:19] op_sel_hi:[1,0,1]
	v_pk_fma_f32 v[4:5], v[92:93], v[12:13], v[20:21] op_sel_hi:[1,0,1]
	v_fmac_f32_e32 v13, v121, v12
	ds_write2_b32 v22, v11, v13 offset1:16
	ds_read_b128 v[58:61], v6 offset:25600
	ds_read_b128 v[62:65], v6 offset:25616
	ds_read_b128 v[66:69], v6 offset:25632
	ds_read_b128 v[70:73], v6 offset:25648
	ds_read_b128 v[74:77], v6 offset:25664
	ds_read2st64_b32 v[118:119], v7 offset0:20 offset1:21
	ds_read_b64 v[120:121], v8 offset:80
	s_waitcnt lgkmcnt(13)
	v_pk_mul_f32 v[14:15], v[2:3], v[98:99] op_sel_hi:[0,1]
	v_pk_fma_f32 v[14:15], v[2:3], v[100:101], v[14:15] op_sel:[1,0,0] op_sel_hi:[1,1,1]
	v_pk_fma_f32 v[14:15], v[4:5], v[102:103], v[14:15] op_sel_hi:[0,1,1]
	v_pk_fma_f32 v[14:15], v[4:5], v[104:105], v[14:15] op_sel:[1,0,0] op_sel_hi:[1,1,1]
	v_pk_mul_f32 v[18:19], v[114:115], v[206:207] op_sel_hi:[1,0]
	v_pk_mul_f32 v[20:21], v[116:117], v[206:207] op_sel_hi:[1,0]
	v_add_f32_dpp v14, v14, v14 quad_perm:[1,0,3,2] row_mask:0xf bank_mask:0xf bound_ctrl:1
	v_add_f32_dpp v15, v15, v15 quad_perm:[1,0,3,2] row_mask:0xf bank_mask:0xf bound_ctrl:1
	v_pk_fma_f32 v[18:19], v[2:3], v[106:107], v[18:19]
	v_add_f32_dpp v14, v14, v14 quad_perm:[2,3,0,1] row_mask:0xf bank_mask:0xf bound_ctrl:1
	v_add_f32_dpp v15, v15, v15 quad_perm:[2,3,0,1] row_mask:0xf bank_mask:0xf bound_ctrl:1
	v_pk_fma_f32 v[20:21], v[4:5], v[108:109], v[20:21]
	v_add_f32_dpp v14, v14, v14 row_half_mirror row_mask:0xf bank_mask:0xf bound_ctrl:1
	v_add_f32_dpp v15, v15, v15 row_half_mirror row_mask:0xf bank_mask:0xf bound_ctrl:1
	s_nop 0
	v_add_f32_dpp v14, v14, v14 row_mirror row_mask:0xf bank_mask:0xf bound_ctrl:1
	v_add_f32_dpp v15, v15, v15 row_mirror row_mask:0xf bank_mask:0xf bound_ctrl:1
	v_pk_fma_f32 v[2:3], v[110:111], v[14:15], v[18:19] op_sel_hi:[1,0,1]
	v_pk_fma_f32 v[4:5], v[112:113], v[14:15], v[20:21] op_sel_hi:[1,0,1]
	v_fmac_f32_e32 v15, v208, v14
	ds_read_b128 v[78:81], v6 offset:26880
	ds_read_b128 v[82:85], v6 offset:26896
	ds_read_b128 v[86:89], v6 offset:26912
	ds_read_b128 v[90:93], v6 offset:26928
	ds_read_b128 v[94:97], v6 offset:26944
	s_waitcnt lgkmcnt(13)
	v_pk_mul_f32 v[16:17], v[2:3], v[186:187] op_sel_hi:[0,1]
	v_pk_fma_f32 v[16:17], v[2:3], v[188:189], v[16:17] op_sel:[1,0,0] op_sel_hi:[1,1,1]
	v_pk_fma_f32 v[16:17], v[4:5], v[190:191], v[16:17] op_sel_hi:[0,1,1]
	v_pk_fma_f32 v[16:17], v[4:5], v[192:193], v[16:17] op_sel:[1,0,0] op_sel_hi:[1,1,1]
	v_pk_mul_f32 v[18:19], v[202:203], v[206:207] op_sel:[0,1] op_sel_hi:[1,1]
	v_pk_mul_f32 v[20:21], v[204:205], v[206:207] op_sel:[0,1] op_sel_hi:[1,1]
	v_add_f32_dpp v16, v16, v16 quad_perm:[1,0,3,2] row_mask:0xf bank_mask:0xf bound_ctrl:1
	v_add_f32_dpp v17, v17, v17 quad_perm:[1,0,3,2] row_mask:0xf bank_mask:0xf bound_ctrl:1
	v_pk_fma_f32 v[18:19], v[2:3], v[194:195], v[18:19]
	v_add_f32_dpp v16, v16, v16 quad_perm:[2,3,0,1] row_mask:0xf bank_mask:0xf bound_ctrl:1
	v_add_f32_dpp v17, v17, v17 quad_perm:[2,3,0,1] row_mask:0xf bank_mask:0xf bound_ctrl:1
	v_pk_fma_f32 v[20:21], v[4:5], v[196:197], v[20:21]
	v_add_f32_dpp v16, v16, v16 row_half_mirror row_mask:0xf bank_mask:0xf bound_ctrl:1
	v_add_f32_dpp v17, v17, v17 row_half_mirror row_mask:0xf bank_mask:0xf bound_ctrl:1
	s_nop 0
	v_add_f32_dpp v16, v16, v16 row_mirror row_mask:0xf bank_mask:0xf bound_ctrl:1
	v_add_f32_dpp v17, v17, v17 row_mirror row_mask:0xf bank_mask:0xf bound_ctrl:1
	v_pk_fma_f32 v[2:3], v[198:199], v[16:17], v[18:19] op_sel_hi:[1,0,1]
	v_pk_fma_f32 v[4:5], v[200:201], v[16:17], v[20:21] op_sel_hi:[1,0,1]
	v_fmac_f32_e32 v17, v209, v16
	ds_write2_b32 v22, v15, v17 offset0:32 offset1:48
	ds_read_b128 v[98:101], v6 offset:28160
	ds_read_b128 v[102:105], v6 offset:28176
	ds_read_b128 v[106:109], v6 offset:28192
	ds_read_b128 v[110:113], v6 offset:28208
	ds_read_b128 v[114:117], v6 offset:28224
	ds_read2st64_b32 v[206:207], v7 offset0:22 offset1:23
	ds_read_b64 v[208:209], v8 offset:88
	s_waitcnt lgkmcnt(13)
	v_pk_mul_f32 v[10:11], v[2:3], v[58:59] op_sel_hi:[0,1]
	v_pk_fma_f32 v[10:11], v[2:3], v[60:61], v[10:11] op_sel:[1,0,0] op_sel_hi:[1,1,1]
	v_pk_fma_f32 v[10:11], v[4:5], v[62:63], v[10:11] op_sel_hi:[0,1,1]
	v_pk_fma_f32 v[10:11], v[4:5], v[64:65], v[10:11] op_sel:[1,0,0] op_sel_hi:[1,1,1]
	v_pk_mul_f32 v[18:19], v[74:75], v[118:119] op_sel_hi:[1,0]
	v_pk_mul_f32 v[20:21], v[76:77], v[118:119] op_sel_hi:[1,0]
	v_add_f32_dpp v10, v10, v10 quad_perm:[1,0,3,2] row_mask:0xf bank_mask:0xf bound_ctrl:1
	v_add_f32_dpp v11, v11, v11 quad_perm:[1,0,3,2] row_mask:0xf bank_mask:0xf bound_ctrl:1
	v_pk_fma_f32 v[18:19], v[2:3], v[66:67], v[18:19]
	v_add_f32_dpp v10, v10, v10 quad_perm:[2,3,0,1] row_mask:0xf bank_mask:0xf bound_ctrl:1
	v_add_f32_dpp v11, v11, v11 quad_perm:[2,3,0,1] row_mask:0xf bank_mask:0xf bound_ctrl:1
	v_pk_fma_f32 v[20:21], v[4:5], v[68:69], v[20:21]
	v_add_f32_dpp v10, v10, v10 row_half_mirror row_mask:0xf bank_mask:0xf bound_ctrl:1
	v_add_f32_dpp v11, v11, v11 row_half_mirror row_mask:0xf bank_mask:0xf bound_ctrl:1
	s_nop 0
	v_add_f32_dpp v10, v10, v10 row_mirror row_mask:0xf bank_mask:0xf bound_ctrl:1
	v_add_f32_dpp v11, v11, v11 row_mirror row_mask:0xf bank_mask:0xf bound_ctrl:1
	v_pk_fma_f32 v[2:3], v[70:71], v[10:11], v[18:19] op_sel_hi:[1,0,1]
	v_pk_fma_f32 v[4:5], v[72:73], v[10:11], v[20:21] op_sel_hi:[1,0,1]
	v_fmac_f32_e32 v11, v120, v10
	ds_read_b128 v[186:189], v6 offset:29440
	ds_read_b128 v[190:193], v6 offset:29456
	ds_read_b128 v[194:197], v6 offset:29472
	ds_read_b128 v[198:201], v6 offset:29488
	ds_read_b128 v[202:205], v6 offset:29504
	s_waitcnt lgkmcnt(13)
	v_pk_mul_f32 v[12:13], v[2:3], v[78:79] op_sel_hi:[0,1]
	v_pk_fma_f32 v[12:13], v[2:3], v[80:81], v[12:13] op_sel:[1,0,0] op_sel_hi:[1,1,1]
	v_pk_fma_f32 v[12:13], v[4:5], v[82:83], v[12:13] op_sel_hi:[0,1,1]
	v_pk_fma_f32 v[12:13], v[4:5], v[84:85], v[12:13] op_sel:[1,0,0] op_sel_hi:[1,1,1]
	v_pk_mul_f32 v[18:19], v[94:95], v[118:119] op_sel:[0,1] op_sel_hi:[1,1]
	v_pk_mul_f32 v[20:21], v[96:97], v[118:119] op_sel:[0,1] op_sel_hi:[1,1]
	v_add_f32_dpp v12, v12, v12 quad_perm:[1,0,3,2] row_mask:0xf bank_mask:0xf bound_ctrl:1
	v_add_f32_dpp v13, v13, v13 quad_perm:[1,0,3,2] row_mask:0xf bank_mask:0xf bound_ctrl:1
	v_pk_fma_f32 v[18:19], v[2:3], v[86:87], v[18:19]
	v_add_f32_dpp v12, v12, v12 quad_perm:[2,3,0,1] row_mask:0xf bank_mask:0xf bound_ctrl:1
	v_add_f32_dpp v13, v13, v13 quad_perm:[2,3,0,1] row_mask:0xf bank_mask:0xf bound_ctrl:1
	v_pk_fma_f32 v[20:21], v[4:5], v[88:89], v[20:21]
	v_add_f32_dpp v12, v12, v12 row_half_mirror row_mask:0xf bank_mask:0xf bound_ctrl:1
	v_add_f32_dpp v13, v13, v13 row_half_mirror row_mask:0xf bank_mask:0xf bound_ctrl:1
	s_nop 0
	v_add_f32_dpp v12, v12, v12 row_mirror row_mask:0xf bank_mask:0xf bound_ctrl:1
	v_add_f32_dpp v13, v13, v13 row_mirror row_mask:0xf bank_mask:0xf bound_ctrl:1
	v_pk_fma_f32 v[2:3], v[90:91], v[12:13], v[18:19] op_sel_hi:[1,0,1]
	v_pk_fma_f32 v[4:5], v[92:93], v[12:13], v[20:21] op_sel_hi:[1,0,1]
	v_fmac_f32_e32 v13, v121, v12
	ds_write2_b32 v22, v11, v13 offset0:64 offset1:80
	ds_read_b128 v[58:61], v6 offset:30720
	ds_read_b128 v[62:65], v6 offset:30736
	ds_read_b128 v[66:69], v6 offset:30752
	ds_read_b128 v[70:73], v6 offset:30768
	ds_read_b128 v[74:77], v6 offset:30784
	ds_read2st64_b32 v[118:119], v7 offset0:24 offset1:25
	ds_read_b64 v[120:121], v8 offset:96
	s_waitcnt lgkmcnt(13)
	v_pk_mul_f32 v[14:15], v[2:3], v[98:99] op_sel_hi:[0,1]
	v_pk_fma_f32 v[14:15], v[2:3], v[100:101], v[14:15] op_sel:[1,0,0] op_sel_hi:[1,1,1]
	v_pk_fma_f32 v[14:15], v[4:5], v[102:103], v[14:15] op_sel_hi:[0,1,1]
	v_pk_fma_f32 v[14:15], v[4:5], v[104:105], v[14:15] op_sel:[1,0,0] op_sel_hi:[1,1,1]
	v_pk_mul_f32 v[18:19], v[114:115], v[206:207] op_sel_hi:[1,0]
	v_pk_mul_f32 v[20:21], v[116:117], v[206:207] op_sel_hi:[1,0]
	v_add_f32_dpp v14, v14, v14 quad_perm:[1,0,3,2] row_mask:0xf bank_mask:0xf bound_ctrl:1
	v_add_f32_dpp v15, v15, v15 quad_perm:[1,0,3,2] row_mask:0xf bank_mask:0xf bound_ctrl:1
	v_pk_fma_f32 v[18:19], v[2:3], v[106:107], v[18:19]
	v_add_f32_dpp v14, v14, v14 quad_perm:[2,3,0,1] row_mask:0xf bank_mask:0xf bound_ctrl:1
	v_add_f32_dpp v15, v15, v15 quad_perm:[2,3,0,1] row_mask:0xf bank_mask:0xf bound_ctrl:1
	v_pk_fma_f32 v[20:21], v[4:5], v[108:109], v[20:21]
	v_add_f32_dpp v14, v14, v14 row_half_mirror row_mask:0xf bank_mask:0xf bound_ctrl:1
	v_add_f32_dpp v15, v15, v15 row_half_mirror row_mask:0xf bank_mask:0xf bound_ctrl:1
	s_nop 0
	v_add_f32_dpp v14, v14, v14 row_mirror row_mask:0xf bank_mask:0xf bound_ctrl:1
	v_add_f32_dpp v15, v15, v15 row_mirror row_mask:0xf bank_mask:0xf bound_ctrl:1
	v_pk_fma_f32 v[2:3], v[110:111], v[14:15], v[18:19] op_sel_hi:[1,0,1]
	v_pk_fma_f32 v[4:5], v[112:113], v[14:15], v[20:21] op_sel_hi:[1,0,1]
	v_fmac_f32_e32 v15, v208, v14
	ds_read_b128 v[78:81], v6 offset:32000
	ds_read_b128 v[82:85], v6 offset:32016
	ds_read_b128 v[86:89], v6 offset:32032
	ds_read_b128 v[90:93], v6 offset:32048
	ds_read_b128 v[94:97], v6 offset:32064
	s_waitcnt lgkmcnt(13)
	v_pk_mul_f32 v[16:17], v[2:3], v[186:187] op_sel_hi:[0,1]
	v_pk_fma_f32 v[16:17], v[2:3], v[188:189], v[16:17] op_sel:[1,0,0] op_sel_hi:[1,1,1]
	v_pk_fma_f32 v[16:17], v[4:5], v[190:191], v[16:17] op_sel_hi:[0,1,1]
	v_pk_fma_f32 v[16:17], v[4:5], v[192:193], v[16:17] op_sel:[1,0,0] op_sel_hi:[1,1,1]
	v_pk_mul_f32 v[18:19], v[202:203], v[206:207] op_sel:[0,1] op_sel_hi:[1,1]
	v_pk_mul_f32 v[20:21], v[204:205], v[206:207] op_sel:[0,1] op_sel_hi:[1,1]
	v_add_f32_dpp v16, v16, v16 quad_perm:[1,0,3,2] row_mask:0xf bank_mask:0xf bound_ctrl:1
	v_add_f32_dpp v17, v17, v17 quad_perm:[1,0,3,2] row_mask:0xf bank_mask:0xf bound_ctrl:1
	v_pk_fma_f32 v[18:19], v[2:3], v[194:195], v[18:19]
	v_add_f32_dpp v16, v16, v16 quad_perm:[2,3,0,1] row_mask:0xf bank_mask:0xf bound_ctrl:1
	v_add_f32_dpp v17, v17, v17 quad_perm:[2,3,0,1] row_mask:0xf bank_mask:0xf bound_ctrl:1
	v_pk_fma_f32 v[20:21], v[4:5], v[196:197], v[20:21]
	v_add_f32_dpp v16, v16, v16 row_half_mirror row_mask:0xf bank_mask:0xf bound_ctrl:1
	v_add_f32_dpp v17, v17, v17 row_half_mirror row_mask:0xf bank_mask:0xf bound_ctrl:1
	s_nop 0
	v_add_f32_dpp v16, v16, v16 row_mirror row_mask:0xf bank_mask:0xf bound_ctrl:1
	v_add_f32_dpp v17, v17, v17 row_mirror row_mask:0xf bank_mask:0xf bound_ctrl:1
	v_pk_fma_f32 v[2:3], v[198:199], v[16:17], v[18:19] op_sel_hi:[1,0,1]
	v_pk_fma_f32 v[4:5], v[200:201], v[16:17], v[20:21] op_sel_hi:[1,0,1]
	v_fmac_f32_e32 v17, v209, v16
	ds_write2_b32 v22, v15, v17 offset0:96 offset1:112
	ds_read_b128 v[98:101], v6 offset:33280
	ds_read_b128 v[102:105], v6 offset:33296
	ds_read_b128 v[106:109], v6 offset:33312
	ds_read_b128 v[110:113], v6 offset:33328
	ds_read_b128 v[114:117], v6 offset:33344
	ds_read2st64_b32 v[206:207], v7 offset0:26 offset1:27
	ds_read_b64 v[208:209], v8 offset:104
	s_waitcnt lgkmcnt(13)
	v_pk_mul_f32 v[10:11], v[2:3], v[58:59] op_sel_hi:[0,1]
	v_pk_fma_f32 v[10:11], v[2:3], v[60:61], v[10:11] op_sel:[1,0,0] op_sel_hi:[1,1,1]
	v_pk_fma_f32 v[10:11], v[4:5], v[62:63], v[10:11] op_sel_hi:[0,1,1]
	v_pk_fma_f32 v[10:11], v[4:5], v[64:65], v[10:11] op_sel:[1,0,0] op_sel_hi:[1,1,1]
	v_pk_mul_f32 v[18:19], v[74:75], v[118:119] op_sel_hi:[1,0]
	v_pk_mul_f32 v[20:21], v[76:77], v[118:119] op_sel_hi:[1,0]
	v_add_f32_dpp v10, v10, v10 quad_perm:[1,0,3,2] row_mask:0xf bank_mask:0xf bound_ctrl:1
	v_add_f32_dpp v11, v11, v11 quad_perm:[1,0,3,2] row_mask:0xf bank_mask:0xf bound_ctrl:1
	v_pk_fma_f32 v[18:19], v[2:3], v[66:67], v[18:19]
	v_add_f32_dpp v10, v10, v10 quad_perm:[2,3,0,1] row_mask:0xf bank_mask:0xf bound_ctrl:1
	v_add_f32_dpp v11, v11, v11 quad_perm:[2,3,0,1] row_mask:0xf bank_mask:0xf bound_ctrl:1
	v_pk_fma_f32 v[20:21], v[4:5], v[68:69], v[20:21]
	v_add_f32_dpp v10, v10, v10 row_half_mirror row_mask:0xf bank_mask:0xf bound_ctrl:1
	v_add_f32_dpp v11, v11, v11 row_half_mirror row_mask:0xf bank_mask:0xf bound_ctrl:1
	s_nop 0
	v_add_f32_dpp v10, v10, v10 row_mirror row_mask:0xf bank_mask:0xf bound_ctrl:1
	v_add_f32_dpp v11, v11, v11 row_mirror row_mask:0xf bank_mask:0xf bound_ctrl:1
	v_pk_fma_f32 v[2:3], v[70:71], v[10:11], v[18:19] op_sel_hi:[1,0,1]
	v_pk_fma_f32 v[4:5], v[72:73], v[10:11], v[20:21] op_sel_hi:[1,0,1]
	v_fmac_f32_e32 v11, v120, v10
	ds_read_b128 v[186:189], v6 offset:34560
	ds_read_b128 v[190:193], v6 offset:34576
	ds_read_b128 v[194:197], v6 offset:34592
	ds_read_b128 v[198:201], v6 offset:34608
	ds_read_b128 v[202:205], v6 offset:34624
	s_waitcnt lgkmcnt(13)
	v_pk_mul_f32 v[12:13], v[2:3], v[78:79] op_sel_hi:[0,1]
	v_pk_fma_f32 v[12:13], v[2:3], v[80:81], v[12:13] op_sel:[1,0,0] op_sel_hi:[1,1,1]
	v_pk_fma_f32 v[12:13], v[4:5], v[82:83], v[12:13] op_sel_hi:[0,1,1]
	v_pk_fma_f32 v[12:13], v[4:5], v[84:85], v[12:13] op_sel:[1,0,0] op_sel_hi:[1,1,1]
	v_pk_mul_f32 v[18:19], v[94:95], v[118:119] op_sel:[0,1] op_sel_hi:[1,1]
	v_pk_mul_f32 v[20:21], v[96:97], v[118:119] op_sel:[0,1] op_sel_hi:[1,1]
	v_add_f32_dpp v12, v12, v12 quad_perm:[1,0,3,2] row_mask:0xf bank_mask:0xf bound_ctrl:1
	v_add_f32_dpp v13, v13, v13 quad_perm:[1,0,3,2] row_mask:0xf bank_mask:0xf bound_ctrl:1
	v_pk_fma_f32 v[18:19], v[2:3], v[86:87], v[18:19]
	v_add_f32_dpp v12, v12, v12 quad_perm:[2,3,0,1] row_mask:0xf bank_mask:0xf bound_ctrl:1
	v_add_f32_dpp v13, v13, v13 quad_perm:[2,3,0,1] row_mask:0xf bank_mask:0xf bound_ctrl:1
	v_pk_fma_f32 v[20:21], v[4:5], v[88:89], v[20:21]
	v_add_f32_dpp v12, v12, v12 row_half_mirror row_mask:0xf bank_mask:0xf bound_ctrl:1
	v_add_f32_dpp v13, v13, v13 row_half_mirror row_mask:0xf bank_mask:0xf bound_ctrl:1
	s_nop 0
	v_add_f32_dpp v12, v12, v12 row_mirror row_mask:0xf bank_mask:0xf bound_ctrl:1
	v_add_f32_dpp v13, v13, v13 row_mirror row_mask:0xf bank_mask:0xf bound_ctrl:1
	v_pk_fma_f32 v[2:3], v[90:91], v[12:13], v[18:19] op_sel_hi:[1,0,1]
	v_pk_fma_f32 v[4:5], v[92:93], v[12:13], v[20:21] op_sel_hi:[1,0,1]
	v_fmac_f32_e32 v13, v121, v12
	ds_write2_b32 v22, v11, v13 offset0:128 offset1:144
	ds_read_b128 v[58:61], v6 offset:35840
	ds_read_b128 v[62:65], v6 offset:35856
	ds_read_b128 v[66:69], v6 offset:35872
	ds_read_b128 v[70:73], v6 offset:35888
	ds_read_b128 v[74:77], v6 offset:35904
	ds_read2st64_b32 v[118:119], v7 offset0:28 offset1:29
	ds_read_b64 v[120:121], v8 offset:112
	s_waitcnt lgkmcnt(13)
	v_pk_mul_f32 v[14:15], v[2:3], v[98:99] op_sel_hi:[0,1]
	v_pk_fma_f32 v[14:15], v[2:3], v[100:101], v[14:15] op_sel:[1,0,0] op_sel_hi:[1,1,1]
	v_pk_fma_f32 v[14:15], v[4:5], v[102:103], v[14:15] op_sel_hi:[0,1,1]
	v_pk_fma_f32 v[14:15], v[4:5], v[104:105], v[14:15] op_sel:[1,0,0] op_sel_hi:[1,1,1]
	v_pk_mul_f32 v[18:19], v[114:115], v[206:207] op_sel_hi:[1,0]
	v_pk_mul_f32 v[20:21], v[116:117], v[206:207] op_sel_hi:[1,0]
	v_add_f32_dpp v14, v14, v14 quad_perm:[1,0,3,2] row_mask:0xf bank_mask:0xf bound_ctrl:1
	v_add_f32_dpp v15, v15, v15 quad_perm:[1,0,3,2] row_mask:0xf bank_mask:0xf bound_ctrl:1
	v_pk_fma_f32 v[18:19], v[2:3], v[106:107], v[18:19]
	v_add_f32_dpp v14, v14, v14 quad_perm:[2,3,0,1] row_mask:0xf bank_mask:0xf bound_ctrl:1
	v_add_f32_dpp v15, v15, v15 quad_perm:[2,3,0,1] row_mask:0xf bank_mask:0xf bound_ctrl:1
	v_pk_fma_f32 v[20:21], v[4:5], v[108:109], v[20:21]
	v_add_f32_dpp v14, v14, v14 row_half_mirror row_mask:0xf bank_mask:0xf bound_ctrl:1
	v_add_f32_dpp v15, v15, v15 row_half_mirror row_mask:0xf bank_mask:0xf bound_ctrl:1
	s_nop 0
	v_add_f32_dpp v14, v14, v14 row_mirror row_mask:0xf bank_mask:0xf bound_ctrl:1
	v_add_f32_dpp v15, v15, v15 row_mirror row_mask:0xf bank_mask:0xf bound_ctrl:1
	v_pk_fma_f32 v[2:3], v[110:111], v[14:15], v[18:19] op_sel_hi:[1,0,1]
	v_pk_fma_f32 v[4:5], v[112:113], v[14:15], v[20:21] op_sel_hi:[1,0,1]
	v_fmac_f32_e32 v15, v208, v14
	ds_read_b128 v[78:81], v6 offset:37120
	ds_read_b128 v[82:85], v6 offset:37136
	ds_read_b128 v[86:89], v6 offset:37152
	ds_read_b128 v[90:93], v6 offset:37168
	ds_read_b128 v[94:97], v6 offset:37184
	s_waitcnt lgkmcnt(13)
	v_pk_mul_f32 v[16:17], v[2:3], v[186:187] op_sel_hi:[0,1]
	v_pk_fma_f32 v[16:17], v[2:3], v[188:189], v[16:17] op_sel:[1,0,0] op_sel_hi:[1,1,1]
	v_pk_fma_f32 v[16:17], v[4:5], v[190:191], v[16:17] op_sel_hi:[0,1,1]
	v_pk_fma_f32 v[16:17], v[4:5], v[192:193], v[16:17] op_sel:[1,0,0] op_sel_hi:[1,1,1]
	v_pk_mul_f32 v[18:19], v[202:203], v[206:207] op_sel:[0,1] op_sel_hi:[1,1]
	v_pk_mul_f32 v[20:21], v[204:205], v[206:207] op_sel:[0,1] op_sel_hi:[1,1]
	v_add_f32_dpp v16, v16, v16 quad_perm:[1,0,3,2] row_mask:0xf bank_mask:0xf bound_ctrl:1
	v_add_f32_dpp v17, v17, v17 quad_perm:[1,0,3,2] row_mask:0xf bank_mask:0xf bound_ctrl:1
	v_pk_fma_f32 v[18:19], v[2:3], v[194:195], v[18:19]
	v_add_f32_dpp v16, v16, v16 quad_perm:[2,3,0,1] row_mask:0xf bank_mask:0xf bound_ctrl:1
	v_add_f32_dpp v17, v17, v17 quad_perm:[2,3,0,1] row_mask:0xf bank_mask:0xf bound_ctrl:1
	v_pk_fma_f32 v[20:21], v[4:5], v[196:197], v[20:21]
	v_add_f32_dpp v16, v16, v16 row_half_mirror row_mask:0xf bank_mask:0xf bound_ctrl:1
	v_add_f32_dpp v17, v17, v17 row_half_mirror row_mask:0xf bank_mask:0xf bound_ctrl:1
	s_nop 0
	v_add_f32_dpp v16, v16, v16 row_mirror row_mask:0xf bank_mask:0xf bound_ctrl:1
	v_add_f32_dpp v17, v17, v17 row_mirror row_mask:0xf bank_mask:0xf bound_ctrl:1
	v_pk_fma_f32 v[2:3], v[198:199], v[16:17], v[18:19] op_sel_hi:[1,0,1]
	v_pk_fma_f32 v[4:5], v[200:201], v[16:17], v[20:21] op_sel_hi:[1,0,1]
	v_fmac_f32_e32 v17, v209, v16
	ds_write2_b32 v22, v15, v17 offset0:160 offset1:176
	ds_read_b128 v[98:101], v6 offset:38400
	ds_read_b128 v[102:105], v6 offset:38416
	ds_read_b128 v[106:109], v6 offset:38432
	ds_read_b128 v[110:113], v6 offset:38448
	ds_read_b128 v[114:117], v6 offset:38464
	ds_read2st64_b32 v[206:207], v7 offset0:30 offset1:31
	ds_read_b64 v[208:209], v8 offset:120
	s_waitcnt lgkmcnt(13)
	v_pk_mul_f32 v[10:11], v[2:3], v[58:59] op_sel_hi:[0,1]
	v_pk_fma_f32 v[10:11], v[2:3], v[60:61], v[10:11] op_sel:[1,0,0] op_sel_hi:[1,1,1]
	v_pk_fma_f32 v[10:11], v[4:5], v[62:63], v[10:11] op_sel_hi:[0,1,1]
	v_pk_fma_f32 v[10:11], v[4:5], v[64:65], v[10:11] op_sel:[1,0,0] op_sel_hi:[1,1,1]
	v_pk_mul_f32 v[18:19], v[74:75], v[118:119] op_sel_hi:[1,0]
	v_pk_mul_f32 v[20:21], v[76:77], v[118:119] op_sel_hi:[1,0]
	v_add_f32_dpp v10, v10, v10 quad_perm:[1,0,3,2] row_mask:0xf bank_mask:0xf bound_ctrl:1
	v_add_f32_dpp v11, v11, v11 quad_perm:[1,0,3,2] row_mask:0xf bank_mask:0xf bound_ctrl:1
	v_pk_fma_f32 v[18:19], v[2:3], v[66:67], v[18:19]
	v_add_f32_dpp v10, v10, v10 quad_perm:[2,3,0,1] row_mask:0xf bank_mask:0xf bound_ctrl:1
	v_add_f32_dpp v11, v11, v11 quad_perm:[2,3,0,1] row_mask:0xf bank_mask:0xf bound_ctrl:1
	v_pk_fma_f32 v[20:21], v[4:5], v[68:69], v[20:21]
	v_add_f32_dpp v10, v10, v10 row_half_mirror row_mask:0xf bank_mask:0xf bound_ctrl:1
	v_add_f32_dpp v11, v11, v11 row_half_mirror row_mask:0xf bank_mask:0xf bound_ctrl:1
	s_nop 0
	v_add_f32_dpp v10, v10, v10 row_mirror row_mask:0xf bank_mask:0xf bound_ctrl:1
	v_add_f32_dpp v11, v11, v11 row_mirror row_mask:0xf bank_mask:0xf bound_ctrl:1
	v_pk_fma_f32 v[2:3], v[70:71], v[10:11], v[18:19] op_sel_hi:[1,0,1]
	v_pk_fma_f32 v[4:5], v[72:73], v[10:11], v[20:21] op_sel_hi:[1,0,1]
	v_fmac_f32_e32 v11, v120, v10
	ds_read_b128 v[186:189], v6 offset:39680
	ds_read_b128 v[190:193], v6 offset:39696
	ds_read_b128 v[194:197], v6 offset:39712
	ds_read_b128 v[198:201], v6 offset:39728
	ds_read_b128 v[202:205], v6 offset:39744
	s_waitcnt lgkmcnt(13)
	v_pk_mul_f32 v[12:13], v[2:3], v[78:79] op_sel_hi:[0,1]
	v_pk_fma_f32 v[12:13], v[2:3], v[80:81], v[12:13] op_sel:[1,0,0] op_sel_hi:[1,1,1]
	v_pk_fma_f32 v[12:13], v[4:5], v[82:83], v[12:13] op_sel_hi:[0,1,1]
	v_pk_fma_f32 v[12:13], v[4:5], v[84:85], v[12:13] op_sel:[1,0,0] op_sel_hi:[1,1,1]
	v_pk_mul_f32 v[18:19], v[94:95], v[118:119] op_sel:[0,1] op_sel_hi:[1,1]
	v_pk_mul_f32 v[20:21], v[96:97], v[118:119] op_sel:[0,1] op_sel_hi:[1,1]
	v_add_f32_dpp v12, v12, v12 quad_perm:[1,0,3,2] row_mask:0xf bank_mask:0xf bound_ctrl:1
	v_add_f32_dpp v13, v13, v13 quad_perm:[1,0,3,2] row_mask:0xf bank_mask:0xf bound_ctrl:1
	v_pk_fma_f32 v[18:19], v[2:3], v[86:87], v[18:19]
	v_add_f32_dpp v12, v12, v12 quad_perm:[2,3,0,1] row_mask:0xf bank_mask:0xf bound_ctrl:1
	v_add_f32_dpp v13, v13, v13 quad_perm:[2,3,0,1] row_mask:0xf bank_mask:0xf bound_ctrl:1
	v_pk_fma_f32 v[20:21], v[4:5], v[88:89], v[20:21]
	v_add_f32_dpp v12, v12, v12 row_half_mirror row_mask:0xf bank_mask:0xf bound_ctrl:1
	v_add_f32_dpp v13, v13, v13 row_half_mirror row_mask:0xf bank_mask:0xf bound_ctrl:1
	s_nop 0
	v_add_f32_dpp v12, v12, v12 row_mirror row_mask:0xf bank_mask:0xf bound_ctrl:1
	v_add_f32_dpp v13, v13, v13 row_mirror row_mask:0xf bank_mask:0xf bound_ctrl:1
	v_pk_fma_f32 v[2:3], v[90:91], v[12:13], v[18:19] op_sel_hi:[1,0,1]
	v_pk_fma_f32 v[4:5], v[92:93], v[12:13], v[20:21] op_sel_hi:[1,0,1]
	v_fmac_f32_e32 v13, v121, v12
	ds_write2_b32 v22, v11, v13 offset0:192 offset1:208
	s_waitcnt lgkmcnt(6)
	v_pk_mul_f32 v[14:15], v[2:3], v[98:99] op_sel_hi:[0,1]
	v_pk_fma_f32 v[14:15], v[2:3], v[100:101], v[14:15] op_sel:[1,0,0] op_sel_hi:[1,1,1]
	v_pk_fma_f32 v[14:15], v[4:5], v[102:103], v[14:15] op_sel_hi:[0,1,1]
	v_pk_fma_f32 v[14:15], v[4:5], v[104:105], v[14:15] op_sel:[1,0,0] op_sel_hi:[1,1,1]
	v_pk_mul_f32 v[18:19], v[114:115], v[206:207] op_sel_hi:[1,0]
	v_pk_mul_f32 v[20:21], v[116:117], v[206:207] op_sel_hi:[1,0]
	v_add_f32_dpp v14, v14, v14 quad_perm:[1,0,3,2] row_mask:0xf bank_mask:0xf bound_ctrl:1
	v_add_f32_dpp v15, v15, v15 quad_perm:[1,0,3,2] row_mask:0xf bank_mask:0xf bound_ctrl:1
	v_pk_fma_f32 v[18:19], v[2:3], v[106:107], v[18:19]
	v_add_f32_dpp v14, v14, v14 quad_perm:[2,3,0,1] row_mask:0xf bank_mask:0xf bound_ctrl:1
	v_add_f32_dpp v15, v15, v15 quad_perm:[2,3,0,1] row_mask:0xf bank_mask:0xf bound_ctrl:1
	v_pk_fma_f32 v[20:21], v[4:5], v[108:109], v[20:21]
	v_add_f32_dpp v14, v14, v14 row_half_mirror row_mask:0xf bank_mask:0xf bound_ctrl:1
	v_add_f32_dpp v15, v15, v15 row_half_mirror row_mask:0xf bank_mask:0xf bound_ctrl:1
	s_nop 0
	v_add_f32_dpp v14, v14, v14 row_mirror row_mask:0xf bank_mask:0xf bound_ctrl:1
	v_add_f32_dpp v15, v15, v15 row_mirror row_mask:0xf bank_mask:0xf bound_ctrl:1
	v_pk_fma_f32 v[2:3], v[110:111], v[14:15], v[18:19] op_sel_hi:[1,0,1]
	v_pk_fma_f32 v[4:5], v[112:113], v[14:15], v[20:21] op_sel_hi:[1,0,1]
	v_fmac_f32_e32 v15, v208, v14
	s_waitcnt lgkmcnt(1)
	v_pk_mul_f32 v[16:17], v[2:3], v[186:187] op_sel_hi:[0,1]
	v_pk_fma_f32 v[16:17], v[2:3], v[188:189], v[16:17] op_sel:[1,0,0] op_sel_hi:[1,1,1]
	v_pk_fma_f32 v[16:17], v[4:5], v[190:191], v[16:17] op_sel_hi:[0,1,1]
	v_pk_fma_f32 v[16:17], v[4:5], v[192:193], v[16:17] op_sel:[1,0,0] op_sel_hi:[1,1,1]
	v_pk_mul_f32 v[18:19], v[202:203], v[206:207] op_sel:[0,1] op_sel_hi:[1,1]
	v_pk_mul_f32 v[20:21], v[204:205], v[206:207] op_sel:[0,1] op_sel_hi:[1,1]
	v_add_f32_dpp v16, v16, v16 quad_perm:[1,0,3,2] row_mask:0xf bank_mask:0xf bound_ctrl:1
	v_add_f32_dpp v17, v17, v17 quad_perm:[1,0,3,2] row_mask:0xf bank_mask:0xf bound_ctrl:1
	v_pk_fma_f32 v[18:19], v[2:3], v[194:195], v[18:19]
	v_add_f32_dpp v16, v16, v16 quad_perm:[2,3,0,1] row_mask:0xf bank_mask:0xf bound_ctrl:1
	v_add_f32_dpp v17, v17, v17 quad_perm:[2,3,0,1] row_mask:0xf bank_mask:0xf bound_ctrl:1
	v_pk_fma_f32 v[20:21], v[4:5], v[196:197], v[20:21]
	v_add_f32_dpp v16, v16, v16 row_half_mirror row_mask:0xf bank_mask:0xf bound_ctrl:1
	v_add_f32_dpp v17, v17, v17 row_half_mirror row_mask:0xf bank_mask:0xf bound_ctrl:1
	s_nop 0
	v_add_f32_dpp v16, v16, v16 row_mirror row_mask:0xf bank_mask:0xf bound_ctrl:1
	v_add_f32_dpp v17, v17, v17 row_mirror row_mask:0xf bank_mask:0xf bound_ctrl:1
	v_pk_fma_f32 v[2:3], v[198:199], v[16:17], v[18:19] op_sel_hi:[1,0,1]
	v_pk_fma_f32 v[4:5], v[200:201], v[16:17], v[20:21] op_sel_hi:[1,0,1]
	v_fmac_f32_e32 v17, v209, v16
	ds_write2_b32 v22, v15, v17 offset0:224 offset1:240
	s_add_i32 s0, s0, 1
	s_cmpk_lg_i32 s0, 0x80
	s_waitcnt lgkmcnt(0)
	s_barrier
	s_cbranch_scc1 .LBB0_726

.LBB0_730:
	s_or_b64 exec, exec, s[0:1]
	v_readlane_b32 s0, v234, 9
	v_readlane_b32 s1, v234, 10
	v_lshl_add_u64 v[6:7], s[34:35], 0, v[36:37]
	v_lshlrev_b64 v[2:3], 11, v[2:3]
	v_mov_b64_e32 v[8:9], s[0:1]
	v_mad_u64_u32 v[8:9], s[0:1], v6, s53, v[8:9]
	v_mad_i32_i24 v9, v7, s53, v9
	v_lshl_add_u64 v[8:9], v[8:9], 0, v[0:1]
	s_movk_i32 s0, 0x1000
	v_add_co_u32_e32 v60, vcc, s0, v8
	s_movk_i32 s0, 0x2000
	s_nop 0
	v_addc_co_u32_e32 v61, vcc, 0, v9, vcc
	v_add_co_u32_e32 v62, vcc, s0, v8
	s_movk_i32 s0, 0xf000
	s_nop 0
	v_addc_co_u32_e32 v63, vcc, 0, v9, vcc
	v_lshl_add_u64 v[4:5], s[10:11], 0, v[2:3]
	v_lshl_add_u64 v[2:3], s[12:13], 0, v[2:3]
	v_add_co_u32_e32 v64, vcc, s0, v8
	v_lshl_add_u64 v[4:5], v[4:5], 0, v[0:1]
	v_lshl_add_u64 v[2:3], v[2:3], 0, v[0:1]
	v_lshl_add_u64 v[58:59], v[8:9], 0, s[28:29]
	v_addc_co_u32_e32 v65, vcc, -1, v9, vcc
	global_load_dwordx2 v[86:87], v[60:61], off offset:1056
	global_load_dwordx2 v[88:89], v[62:63], off offset:1056
	global_load_dwordx2 v[98:99], v[64:65], off offset:-3040
	global_load_dwordx2 v[94:95], v[64:65], off offset:-992
	global_load_dwordx2 v[122:123], v[4:5], off
	global_load_dwordx2 v[120:121], v[2:3], off
	global_load_dwordx2 v[96:97], v[58:59], off offset:2048
	global_load_dwordx2 v[92:93], v[8:9], off offset:-3040
	v_lshlrev_b64 v[2:3], 11, v[6:7]
	v_lshl_add_u64 v[4:5], s[10:11], 0, v[2:3]
	v_lshl_add_u64 v[4:5], v[4:5], 0, v[0:1]
	v_lshl_add_u64 v[2:3], s[12:13], 0, v[2:3]
	v_lshl_add_u64 v[2:3], v[2:3], 0, v[0:1]
	global_load_dwordx2 v[90:91], v[4:5], off
	global_load_dwordx2 v[84:85], v[2:3], off
	s_lshr_b32 s0, s59, 2
	s_and_b32 s0, s0, 15
	s_lshl_b32 s40, s0, 2
	s_cmp_eq_u32 s59, s71
	v_lshlrev_b32_e32 v0, 1, v43
	s_cselect_b64 s[36:37], -1, 0
	s_cmp_eq_u32 s16, 0
	v_lshl_or_b32 v2, s0, 7, v0
	s_cselect_b64 s[38:39], -1, 0
	s_lshl_b32 s0, s60, 1
	s_add_u32 s0, s14, s0
	s_addc_u32 s1, s15, 0
	s_lshl_b32 s61, s16, 4
	s_lshl_b32 s16, s16, 5
	s_add_u32 s0, s0, s16
	s_addc_u32 s1, s1, 0
	v_lshlrev_b32_e32 v58, 1, v46
	v_mov_b32_e32 v59, v1
	v_lshl_add_u64 v[72:73], s[0:1], 0, v[58:59]
	s_lshl_b64 s[0:1], s[8:9], 18
	s_or_b32 s0, s0, s40
	v_lshl_add_u64 v[78:79], s[0:1], 0, v[50:51]
	s_lshl_b64 s[0:1], s[8:9], 23
	v_mov_b32_e32 v3, v1
	v_lshl_add_u64 v[4:5], v[52:53], 0, s[0:1]
	v_lshl_add_u64 v[80:81], v[4:5], 0, v[2:3]
	v_mad_i64_i32 v[4:5], s[0:1], s8, v152, v[54:55]
	v_lshl_add_u64 v[82:83], v[4:5], 0, v[2:3]
	v_mov_b32_e32 v2, v1
	v_mov_b32_e32 v4, v1
	v_mov_b32_e32 v5, v1
	v_mov_b32_e32 v6, v1
	v_mov_b32_e32 v7, v1
	v_mov_b32_e32 v0, v1
	v_mov_b64_e32 v[8:9], v[6:7]
	s_mov_b32 s62, 0
	v_lshl_add_u64 v[70:71], s[34:35], 0, v[44:45]
	s_waitcnt vmcnt(17)
	v_mov_b32_e32 v74, v16
	s_waitcnt vmcnt(13)
	v_mov_b32_e32 v75, v33
	v_mov_b32_e32 v76, v29
	v_mov_b32_e32 v77, v57
	v_mov_b64_e32 v[62:63], 0
	s_movk_i32 s16, 0xffc0
	v_mov_b32_e32 v67, 0
	v_mov_b32_e32 v33, 0
	v_mov_b32_e32 v68, 0
	v_mov_b32_e32 v66, 0
	v_mov_b32_e32 v59, 0
	v_mov_b32_e32 v29, v47
	s_mov_b32 s63, 0
	v_mov_b64_e32 v[6:7], v[4:5]
	v_mov_b64_e32 v[4:5], v[2:3]
	v_mov_b64_e32 v[2:3], v[0:1]
	v_mov_b64_e32 v[64:65], 0
	v_mov_b64_e32 v[60:61], 0
	s_waitcnt vmcnt(0)
	v_subrev_u32_e32 v217, 0x100, v170
	v_lshrrev_b32_e32 v218, 3, v217
	v_and_b32_e32 v217, 7, v217
	v_mov_b32_e32 v216, s59
	v_and_b32_e32 v216, 3, v216
	v_lshlrev_b32_e32 v215, 8, v218
	v_lshl_add_u32 v215, v216, 6, v215
	v_lshl_add_u32 v215, v217, 3, v215
	v_add_u32_e32 v215, 0x14000, v215
	v_lshlrev_b32_e32 v216, 2, v218
	v_add_u32_e32 v216, 0x18080, v216

.LBB0_768:
	v_lshlrev_b32_e32 v162, 16, v122
	v_lshlrev_b32_e32 v154, 16, v100
	v_and_b32_e32 v155, 0xffff0000, v100
	v_lshlrev_b32_e32 v56, 16, v101
	v_lshlrev_b32_e32 v16, 16, v111
	v_lshlrev_b32_e32 v163, 16, v105
	v_and_b32_e32 v100, 0xffff0000, v105
	v_lshlrev_b32_e32 v158, 16, v104
	v_and_b32_e32 v159, 0xffff0000, v104
	v_lshlrev_b32_e32 v104, 16, v108
	v_and_b32_e32 v105, 0xffff0000, v108
	v_lshlrev_b32_e32 v153, 16, v109
	v_and_b32_e32 v167, 0xffff0000, v122
	v_and_b32_e32 v165, 0xffff0000, v101
	v_mul_f32_e32 v101, 0xbfb8aa3b, v162
	v_lshlrev_b32_e32 v156, 16, v110
	v_and_b32_e32 v157, 0xffff0000, v110
	v_and_b32_e32 v161, 0xffff0000, v111
	v_and_b32_e32 v160, 0xffff0000, v109
	v_lshlrev_b32_e32 v108, 16, v102
	v_and_b32_e32 v109, 0xffff0000, v102
	v_lshlrev_b32_e32 v110, 16, v106
	v_and_b32_e32 v111, 0xffff0000, v106
	v_lshlrev_b32_e32 v173, 16, v123
	v_and_b32_e32 v123, 0xffff0000, v123
	v_pk_add_f32 v[168:169], v[104:105], v[158:159] neg_lo:[0,1] neg_hi:[0,1]
	v_exp_f32_e32 v104, v101
	v_mul_f32_e32 v101, 0xbfb8aa3b, v167
	v_sub_f32_e32 v172, v16, v56
	v_sub_f32_e32 v16, v153, v163
	v_lshlrev_b32_e32 v102, 16, v103
	v_and_b32_e32 v103, 0xffff0000, v103
	v_lshlrev_b32_e32 v106, 16, v107
	v_and_b32_e32 v107, 0xffff0000, v107
	v_lshlrev_b32_e32 v184, 16, v121
	v_pk_add_f32 v[110:111], v[110:111], v[108:109] neg_lo:[0,1] neg_hi:[0,1]
	v_exp_f32_e32 v105, v101
	v_fmac_f32_e32 v163, v24, v16
	v_mul_f32_e32 v16, 0xbfb8aa3b, v173
	v_mul_f32_e32 v101, 0xbfb8aa3b, v123
	v_pk_fma_f32 v[108:109], v[18:19], v[110:111], v[108:109]
	v_pk_add_f32 v[110:111], v[106:107], v[102:103] neg_lo:[0,1] neg_hi:[0,1]
	v_exp_f32_e32 v106, v16
	v_sub_f32_e32 v16, v160, v100
	v_exp_f32_e32 v107, v101
	v_add_f32_e32 v101, -1.0, v184
	v_pk_fma_f32 v[110:111], v[20:21], v[110:111], v[102:103]
	v_pk_add_f32 v[102:103], v[156:157], v[154:155] neg_lo:[0,1] neg_hi:[0,1]
	v_mul_f32_e32 v101, v32, v101
	v_fmac_f32_e32 v100, v25, v16
	v_pk_fma_f32 v[102:103], v[14:15], v[102:103], v[154:155]
	v_pk_mul_f32 v[156:157], v[76:77], v[100:101]
	v_pk_add_f32 v[154:155], v[76:77], v[100:101]
	v_mul_f32_e32 v175, v28, v163
	v_mov_b32_e32 v157, v155
	v_pk_fma_f32 v[154:155], v[22:23], v[168:169], v[158:159]
	v_mov_b32_e32 v174, v156
	v_pk_mul_f32 v[158:159], v[26:27], v[154:155]
	v_pk_mul_f32 v[176:177], v[174:175], v[174:175]
	v_pk_mul_f32 v[168:169], v[158:159], v[158:159]
	v_and_b32_e32 v164, 0xffff0000, v120
	v_add_f32_e32 v101, v168, v169
	v_add_f32_e32 v101, v177, v101
	v_add_f32_e32 v101, v176, v101
	v_pk_mov_b32 v[178:179], v[164:165], v[164:165] op_sel:[1,0]
	v_lshlrev_b32_e32 v122, 16, v120
	v_add_f32_dpp v101, v101, v101 quad_perm:[1,0,3,2] row_mask:0xf bank_mask:0xf bound_ctrl:1
	v_mov_b32_e32 v123, v179
	v_pk_add_f32 v[180:181], v[122:123], -1.0 op_sel_hi:[1,0]
	v_add_f32_dpp v101, v101, v101 quad_perm:[2,3,0,1] row_mask:0xf bank_mask:0xf bound_ctrl:1
	v_and_b32_e32 v166, 0xffff0000, v121
	v_pk_fma_f32 v[180:181], v[30:31], v[180:181], 1.0 op_sel_hi:[1,1,0]
	v_add_f32_dpp v101, v101, v101 row_half_mirror row_mask:0xf bank_mask:0xf bound_ctrl:1
	v_add_f32_e32 v173, -1.0, v166
	v_pk_mul_f32 v[154:155], v[180:181], v[154:155]
	v_add_f32_dpp v101, v101, v101 row_mirror row_mask:0xf bank_mask:0xf bound_ctrl:1
	v_max_f32_e32 v101, 0x179abe15, v101
	v_rsq_f32_e32 v162, v101
	v_mov_b32_e32 v16, v103
	v_pk_fma_f32 v[172:173], v[74:75], v[172:173], v[56:57]
	v_fma_f32 v179, v154, v102, 0
	v_pk_mul_f32 v[168:169], v[158:159], v[162:163] op_sel_hi:[1,0]
	v_mov_b32_e32 v180, v17
	v_mov_b32_e32 v160, v169
	v_mul_f32_e32 v158, v168, v122
	v_pk_mul_f32 v[176:177], v[160:161], v[164:165]
	v_pk_add_f32 v[160:161], v[160:161], v[164:165] neg_lo:[0,1] neg_hi:[0,1]
	v_fma_f32 v122, v102, v158, 0
	v_mov_b32_e32 v177, v161
	v_mov_b32_e32 v181, v155
	v_mov_b32_e32 v160, v161
	v_mov_b32_e32 v161, v103
	v_mov_b32_e32 v123, v165
	v_mov_b32_e32 v167, v172
	v_mul_f32_e32 v56, v154, v102
	v_pk_fma_f32 v[182:183], v[16:17], v[176:177], v[122:123]
	v_pk_fma_f32 v[178:179], v[180:181], v[160:161], v[178:179]
	v_pk_mul_f32 v[180:181], v[156:157], v[162:163]
	v_mul_f32_e64 v164, v175, -v162
	v_pk_mul_f32 v[120:121], v[104:105], v[102:103]
	v_fma_f32 v56, v10, v56, 0
	v_pk_mul_f32 v[102:103], v[154:155], v[102:103]
	v_mul_f32_e64 v160, -v164, v184
	v_pk_mul_f32 v[174:175], v[180:181], v[166:167]
	v_mov_b32_e32 v161, v100
	v_mov_b32_e32 v100, v172
	v_mov_b32_e32 v101, v183
	v_fmac_f32_e32 v56, v11, v103
	v_pk_mul_f32 v[156:157], v[172:173], v[160:161]
	v_pk_mul_f32 v[122:123], v[106:107], v[100:101]
	v_pk_mul_f32 v[100:101], v[178:179], v[174:175]
	v_pk_fma_f32 v[102:103], v[180:181], v[166:167], v[178:179]
	v_pk_mul_f32 v[162:163], v[156:157], v[182:183]
	v_mov_b32_e32 v101, v103
	v_pk_fma_f32 v[102:103], v[172:173], v[160:161], v[182:183]
	s_and_b32 s0, s63, 1
	v_mov_b32_e32 v103, v163
	v_pk_add_f32 v[100:101], v[102:103], v[100:101]
	s_mul_i32 s1, s0, 0xa000
	v_fmac_f32_e32 v56, v12, v175
	v_mov_b32_dpp v102, v100 quad_perm:[1,0,3,2] row_mask:0xf bank_mask:0xf bound_ctrl:1
	v_mov_b32_dpp v103, v101 quad_perm:[1,0,3,2] row_mask:0xf bank_mask:0xf bound_ctrl:1
	v_pk_add_f32 v[100:101], v[100:101], v[102:103]
	v_add_u32_e32 v69, s1, v138
	v_fmac_f32_e32 v56, v13, v163
	v_mov_b32_dpp v102, v100 quad_perm:[2,3,0,1] row_mask:0xf bank_mask:0xf bound_ctrl:1
	v_mov_b32_dpp v103, v101 quad_perm:[2,3,0,1] row_mask:0xf bank_mask:0xf bound_ctrl:1
	v_lshl_add_u32 v0, s0, 13, v136
	v_add_u32_e32 v69, v69, v145
	v_pk_add_f32 v[100:101], v[100:101], v[102:103]
	v_add_f32_dpp v16, v56, v56 quad_perm:[1,0,3,2] row_mask:0xf bank_mask:0xf bound_ctrl:1
	v_xor_b32_e32 v163, 0x80000000, v169
	v_xor_b32_e32 v162, 0x80000000, v168
	v_xor_b32_e32 v165, 0x80000000, v180
	s_lshl_b32 s8, s0, 8
	v_mov_b32_dpp v102, v100 row_half_mirror row_mask:0xf bank_mask:0xf bound_ctrl:1
	v_mov_b32_dpp v103, v101 row_half_mirror row_mask:0xf bank_mask:0xf bound_ctrl:1
	v_add_f32_dpp v16, v16, v16 quad_perm:[2,3,0,1] row_mask:0xf bank_mask:0xf bound_ctrl:1
	ds_write2_b32 v69, v162, v120 offset1:1
	ds_write2_b32 v69, v163, v121 offset0:2 offset1:3
	ds_write2_b32 v69, v164, v122 offset0:4 offset1:5
	ds_write2_b32 v69, v165, v123 offset0:6 offset1:7
	ds_write_b128 v69, v[104:107] offset:32
	v_mov_b32_e32 v159, v176
	v_mov_b32_e32 v161, v174
	v_mov_b32_e32 v156, v181
	v_add_u32_e32 v104, v0, v146
	s_add_i32 s46, s8, 0
	v_pk_add_f32 v[100:101], v[100:101], v[102:103]
	v_add_f32_dpp v16, v16, v16 row_half_mirror row_mask:0xf bank_mask:0xf bound_ctrl:1
	ds_write_b128 v69, v[158:161] offset:48
	ds_write_b128 v69, v[154:157] offset:64
	ds_write_b128 v104, v[108:111]
	v_cndmask_b32_e64 v104, 0, 1, s[38:39]
	s_add_i32 s46, s46, 0x18000
	v_mov_b32_dpp v102, v100 row_mirror row_mask:0xf bank_mask:0xf bound_ctrl:1
	v_mov_b32_dpp v103, v101 row_mirror row_mask:0xf bank_mask:0xf bound_ctrl:1
	v_mov_b32_dpp v56, v16 row_mirror row_mask:0xf bank_mask:0xf bound_ctrl:1
	v_cmp_ne_u32_e64 s[8:9], 1, v104
	s_and_saveexec_b64 s[0:1], s[6:7]
	s_cbranch_execz .LBB0_771
	v_lshrrev_b32_e32 v104, 1, v147
	v_add_u32_e32 v104, s46, v104
	v_pk_add_f32 v[100:101], v[100:101], v[102:103]
	s_and_b64 vcc, exec, s[8:9]
	ds_write2_b32 v104, v100, v101 offset1:32
	s_cbranch_vccnz .LBB0_771
	v_lshl_add_u64 v[100:101], s[66:67], 0, v[78:79]
	v_add_co_u32_e32 v100, vcc, 0x1f000000, v100
	v_add_f32_e32 v16, v16, v56
	s_nop 0
	v_addc_co_u32_e32 v101, vcc, 0, v101, vcc
	global_store_dword v[100:101], v16, off

.LBB0_773:
	v_lshlrev_b32_e32 v132, 16, v86
	v_and_b32_e32 v133, 0xffff0000, v86
	v_lshlrev_b32_e32 v134, 16, v98
	v_and_b32_e32 v135, 0xffff0000, v98
	v_lshlrev_b32_e32 v157, 16, v97
	v_and_b32_e32 v86, 0xffff0000, v97
	v_lshlrev_b32_e32 v154, 16, v96
	v_and_b32_e32 v155, 0xffff0000, v96
	v_lshlrev_b32_e32 v96, 16, v94
	v_and_b32_e32 v97, 0xffff0000, v94
	v_lshlrev_b32_e32 v98, 16, v95
	v_and_b32_e32 v153, 0xffff0000, v95
	v_lshlrev_b32_e32 v94, 16, v88
	v_and_b32_e32 v95, 0xffff0000, v88
	v_lshlrev_b32_e32 v88, 16, v90
	v_lshlrev_b32_e32 v56, 16, v87
	v_lshlrev_b32_e32 v16, 16, v99
	v_lshlrev_b32_e32 v158, 16, v92
	v_and_b32_e32 v159, 0xffff0000, v92
	v_lshlrev_b32_e32 v160, 16, v89
	v_and_b32_e32 v161, 0xffff0000, v89
	v_and_b32_e32 v89, 0xffff0000, v90
	v_lshlrev_b32_e32 v164, 16, v84
	v_and_b32_e32 v166, 0xffff0000, v84
	v_lshlrev_b32_e32 v178, 16, v85
	v_and_b32_e32 v84, 0xffff0000, v85
	v_mul_f32_e32 v85, 0xbfb8aa3b, v88
	v_lshlrev_b32_e32 v156, 16, v91
	v_and_b32_e32 v165, 0xffff0000, v91
	v_pk_add_f32 v[90:91], v[158:159], v[94:95] neg_lo:[0,1] neg_hi:[0,1]
	v_exp_f32_e32 v88, v85
	v_mul_f32_e32 v85, 0xbfb8aa3b, v89
	v_sub_f32_e32 v158, v16, v56
	v_sub_f32_e32 v16, v98, v157
	v_exp_f32_e32 v89, v85
	v_fmac_f32_e32 v157, v24, v16
	v_mul_f32_e32 v16, 0xbfb8aa3b, v156
	v_mul_f32_e32 v85, 0xbfb8aa3b, v165
	v_lshlrev_b32_e32 v162, 16, v93
	v_and_b32_e32 v163, 0xffff0000, v93
	v_pk_fma_f32 v[92:93], v[18:19], v[90:91], v[94:95]
	v_exp_f32_e32 v90, v16
	v_sub_f32_e32 v16, v153, v86
	v_exp_f32_e32 v91, v85
	v_add_f32_e32 v85, -1.0, v178
	v_and_b32_e32 v167, 0xffff0000, v87
	v_pk_add_f32 v[168:169], v[96:97], v[154:155] neg_lo:[0,1] neg_hi:[0,1]
	v_pk_add_f32 v[94:95], v[162:163], v[160:161] neg_lo:[0,1] neg_hi:[0,1]
	v_pk_add_f32 v[96:97], v[134:135], v[132:133] neg_lo:[0,1] neg_hi:[0,1]
	v_mul_f32_e32 v87, v32, v85
	v_fmac_f32_e32 v86, v25, v16
	v_pk_fma_f32 v[94:95], v[20:21], v[94:95], v[160:161]
	v_pk_fma_f32 v[134:135], v[14:15], v[96:97], v[132:133]
	v_pk_mul_f32 v[160:161], v[76:77], v[86:87]
	v_pk_add_f32 v[132:133], v[76:77], v[86:87]
	v_mul_f32_e32 v163, v28, v157
	v_mov_b32_e32 v161, v133
	v_pk_fma_f32 v[132:133], v[22:23], v[168:169], v[154:155]
	v_mov_b32_e32 v162, v160
	v_pk_mul_f32 v[154:155], v[26:27], v[132:133]
	v_pk_mul_f32 v[172:173], v[162:163], v[162:163]
	v_pk_mul_f32 v[168:169], v[154:155], v[154:155]
	v_pk_mov_b32 v[174:175], v[166:167], v[166:167] op_sel:[1,0]
	v_add_f32_e32 v87, v168, v169
	v_add_f32_e32 v87, v173, v87
	v_add_f32_e32 v87, v172, v87
	v_mov_b32_e32 v165, v175
	v_pk_add_f32 v[176:177], v[164:165], -1.0 op_sel_hi:[1,0]
	v_add_f32_dpp v87, v87, v87 quad_perm:[1,0,3,2] row_mask:0xf bank_mask:0xf bound_ctrl:1
	v_and_b32_e32 v99, 0xffff0000, v99
	v_pk_fma_f32 v[176:177], v[30:31], v[176:177], 1.0 op_sel_hi:[1,1,0]
	v_add_f32_dpp v87, v87, v87 quad_perm:[2,3,0,1] row_mask:0xf bank_mask:0xf bound_ctrl:1
	v_add_f32_e32 v159, -1.0, v84
	v_pk_mul_f32 v[132:133], v[176:177], v[132:133]
	v_add_f32_dpp v87, v87, v87 row_half_mirror row_mask:0xf bank_mask:0xf bound_ctrl:1
	v_mov_b32_e32 v16, v135
	v_pk_fma_f32 v[158:159], v[74:75], v[158:159], v[56:57]
	v_add_f32_dpp v87, v87, v87 row_mirror row_mask:0xf bank_mask:0xf bound_ctrl:1
	v_max_f32_e32 v87, 0x179abe15, v87
	v_rsq_f32_e32 v156, v87
	v_fma_f32 v175, v132, v134, 0
	v_mov_b32_e32 v176, v17
	v_mov_b32_e32 v177, v133
	v_pk_mul_f32 v[168:169], v[154:155], v[156:157] op_sel_hi:[1,0]
	v_mov_b32_e32 v165, v167
	v_mov_b32_e32 v98, v169
	v_mul_f32_e32 v154, v168, v164
	v_pk_mul_f32 v[172:173], v[98:99], v[166:167]
	v_pk_add_f32 v[98:99], v[98:99], v[166:167] neg_lo:[0,1] neg_hi:[0,1]
	v_fma_f32 v164, v134, v154, 0
	v_mov_b32_e32 v173, v99
	v_mov_b32_e32 v98, v99
	v_mov_b32_e32 v99, v135
	v_mov_b32_e32 v85, v158
	v_mul_f32_e32 v56, v132, v134
	v_pk_fma_f32 v[164:165], v[16:17], v[172:173], v[164:165]
	v_pk_fma_f32 v[166:167], v[176:177], v[98:99], v[174:175]
	v_pk_mul_f32 v[174:175], v[160:161], v[156:157]
	v_mul_f32_e64 v160, v163, -v156
	v_pk_mul_f32 v[96:97], v[88:89], v[134:135]
	v_fma_f32 v56, v10, v56, 0
	v_pk_mul_f32 v[134:135], v[132:133], v[134:135]
	v_mul_f32_e64 v156, -v160, v178
	v_pk_mul_f32 v[162:163], v[174:175], v[84:85]
	v_mov_b32_e32 v157, v86
	v_mov_b32_e32 v86, v158
	v_mov_b32_e32 v87, v165
	v_fmac_f32_e32 v56, v11, v135
	v_pk_mul_f32 v[134:135], v[158:159], v[156:157]
	v_pk_mul_f32 v[98:99], v[90:91], v[86:87]
	v_pk_mul_f32 v[86:87], v[166:167], v[162:163]
	v_pk_fma_f32 v[84:85], v[174:175], v[84:85], v[166:167]
	v_fmac_f32_e32 v56, v12, v163
	v_mov_b32_e32 v87, v85
	v_pk_fma_f32 v[84:85], v[158:159], v[156:157], v[164:165]
	v_pk_mul_f32 v[158:159], v[134:135], v[164:165]
	v_xor_b32_e32 v161, 0x80000000, v174
	v_mov_b32_e32 v85, v159
	v_pk_add_f32 v[84:85], v[84:85], v[86:87]
	v_fmac_f32_e32 v56, v13, v159
	v_xor_b32_e32 v159, 0x80000000, v169
	v_mov_b32_dpp v86, v84 quad_perm:[1,0,3,2] row_mask:0xf bank_mask:0xf bound_ctrl:1
	v_mov_b32_dpp v87, v85 quad_perm:[1,0,3,2] row_mask:0xf bank_mask:0xf bound_ctrl:1
	v_pk_add_f32 v[84:85], v[84:85], v[86:87]
	v_add_f32_dpp v16, v56, v56 quad_perm:[1,0,3,2] row_mask:0xf bank_mask:0xf bound_ctrl:1
	v_xor_b32_e32 v158, 0x80000000, v168
	v_mov_b32_dpp v86, v84 quad_perm:[2,3,0,1] row_mask:0xf bank_mask:0xf bound_ctrl:1
	v_mov_b32_dpp v87, v85 quad_perm:[2,3,0,1] row_mask:0xf bank_mask:0xf bound_ctrl:1
	v_pk_add_f32 v[84:85], v[84:85], v[86:87]
	v_add_f32_dpp v16, v16, v16 quad_perm:[2,3,0,1] row_mask:0xf bank_mask:0xf bound_ctrl:1
	v_mov_b32_e32 v155, v172
	v_mov_b32_dpp v86, v84 row_half_mirror row_mask:0xf bank_mask:0xf bound_ctrl:1
	v_mov_b32_dpp v87, v85 row_half_mirror row_mask:0xf bank_mask:0xf bound_ctrl:1
	v_pk_add_f32 v[84:85], v[84:85], v[86:87]
	v_add_f32_dpp v16, v16, v16 row_half_mirror row_mask:0xf bank_mask:0xf bound_ctrl:1
	v_mov_b32_e32 v157, v162
	v_mov_b32_dpp v86, v84 row_mirror row_mask:0xf bank_mask:0xf bound_ctrl:1
	v_mov_b32_dpp v87, v85 row_mirror row_mask:0xf bank_mask:0xf bound_ctrl:1
	v_mov_b32_dpp v56, v16 row_mirror row_mask:0xf bank_mask:0xf bound_ctrl:1
	v_mov_b32_e32 v134, v175
	v_add_u32_e32 v0, v0, v148
	v_add_u32_e32 v253, 0x5000, v69
	ds_write2_b32 v253, v158, v96 offset1:1
	ds_write2_b32 v253, v159, v97 offset0:2 offset1:3
	ds_write2_b32 v253, v160, v98 offset0:4 offset1:5
	ds_write2_b32 v253, v161, v99 offset0:6 offset1:7
	ds_write_b128 v69, v[88:91] offset:20512
	ds_write_b128 v69, v[154:157] offset:20528
	ds_write_b128 v69, v[132:135] offset:20544
	ds_write_b128 v0, v[92:95]
	s_and_saveexec_b64 s[0:1], s[6:7]
	s_cbranch_execz .LBB0_776
	v_lshrrev_b32_e32 v0, 1, v149
	v_add_u32_e32 v0, s46, v0
	v_pk_add_f32 v[84:85], v[84:85], v[86:87]
	s_and_b64 vcc, exec, s[8:9]
	ds_write2_b32 v0, v84, v85 offset1:32
	s_cbranch_vccnz .LBB0_776
	v_lshl_add_u64 v[84:85], s[66:67], 0, v[78:79]
	v_add_co_u32_e32 v84, vcc, 0x1f000000, v84
	v_add_f32_e32 v0, v16, v56
	s_nop 0
	v_addc_co_u32_e32 v85, vcc, 0, v85, vcc
	global_store_dword v[84:85], v0, off offset:1024
